# candI + stagger: waves 4-7 start the PEER step A and step B loops half an iteration (s_sleep 39) after their SIMD partners
# speedup vs baseline: 1.0209x; 1.0115x over previous
; __device__ __forceinline__ f32x2 fp8x2_lo(unsigned w) { return __builtin_amdgcn_cvt_pk_f32_fp8(w, false); }
; __device__ __forceinline__ f32x2 fp8x2_hi(unsigned w) { return __builtin_amdgcn_cvt_pk_f32_fp8(w, true); }
; #define PA_IDS(T) do { const unsigned* kp_ = KP + (size_t)(T) * 256; _Pragma("unroll") for (int qq = 0; qq < 4; ++qq) idv[qq] = *(const u32x4*)(kp_ + 4 * qq); } while (0)
; template <bool NT>
; __device__ __forceinline__ void peer_passA(const Args& a, const PeerWork w) {
;     ...
;     int t = peer_tok(w, q), t1 = peer_tok(w, min(q + qs, ql));
;     PA_IDS(t);
;     PA_GATHER(t, ur, hv);
;     PA_IDS(t1);
; #pragma unroll 1
;     for (;; q += qs) {
;         u32x4 urn[16]; f32x4 hn[4];
;         PA_GATHER(t1, urn, hn);
;         const int t2 = peer_tok(w, min(q + 2 * qs, ql));
;         PA_IDS(t2);
;         float part[16];
; #pragma unroll
;         for (int k = 0; k < 16; ++k) {
;             const unsigned ww[4] = {ur[k].x, ur[k].y, ur[k].z, ur[k].w};
;             f32x2 p2 = {0.f, 0.f};
; #pragma unroll
;             for (int wd = 0; wd < 4; ++wd) { p2 = __builtin_elementwise_fma(fp8x2_lo(ww[wd]), (f32x2){hv[wd][0], hv[wd][1]}, p2); p2 = __builtin_elementwise_fma(fp8x2_hi(ww[wd]), (f32x2){hv[wd][2], hv[wd][3]}, p2); }
;             part[k] = p2[0] + p2[1];
.Lpa_pre_a6:
	s_waitcnt vmcnt(0)
	v_mov_b64_e32 v[182:183], v[4:5]
	v_mov_b64_e32 v[180:181], v[2:3]
	v_mov_b64_e32 v[178:179], v[8:9]
	v_mov_b64_e32 v[176:177], v[6:7]
	v_mov_b64_e32 v[174:175], v[12:13]
	v_mov_b64_e32 v[172:173], v[10:11]
	v_mov_b64_e32 v[170:171], v[16:17]
	v_mov_b64_e32 v[168:169], v[14:15]
	v_mov_b64_e32 v[166:167], v[24:25]
	v_mov_b64_e32 v[164:165], v[22:23]
	v_mov_b64_e32 v[162:163], v[28:29]
	v_mov_b64_e32 v[160:161], v[26:27]
	v_mov_b64_e32 v[152:153], v[36:37]
	v_mov_b64_e32 v[150:151], v[34:35]
	v_mov_b64_e32 v[148:149], v[40:41]
	v_mov_b64_e32 v[146:147], v[38:39]
	v_mov_b64_e32 v[144:145], v[44:45]
	v_mov_b64_e32 v[142:143], v[42:43]
	v_mov_b64_e32 v[140:141], v[48:49]
	v_mov_b64_e32 v[138:139], v[46:47]
	v_mov_b64_e32 v[136:137], v[56:57]
	v_mov_b64_e32 v[134:135], v[54:55]
	v_mov_b64_e32 v[132:133], v[60:61]
	v_mov_b64_e32 v[130:131], v[58:59]
	v_mov_b64_e32 v[128:129], v[68:69]
	v_mov_b64_e32 v[126:127], v[66:67]
	v_mov_b64_e32 v[124:125], v[72:73]
	v_mov_b64_e32 v[116:117], v[80:81]
	v_mov_b64_e32 v[120:121], v[76:77]
	v_mov_b64_e32 v[122:123], v[70:71]
	v_mov_b64_e32 v[114:115], v[78:79]
	v_mov_b64_e32 v[118:119], v[74:75]
	s_cmp_lt_u32 s42, 4
	s_cbranch_scc1 .Lstag_a
	s_sleep 39
.Lstag_a:
.LBB0_1321:
	s_waitcnt vmcnt(24)
	v_cvt_pk_f32_fp8_e32 v[184:185], v180
	v_cvt_pk_f32_fp8_sdwa v[186:187], v180 src0_sel:WORD_1
	v_cvt_pk_f32_fp8_e32 v[188:189], v181
	v_cvt_pk_f32_fp8_sdwa v[180:181], v181 src0_sel:WORD_1
	s_waitcnt vmcnt(5)
	v_pk_fma_f32 v[184:185], v[184:185], v[94:95], 0 op_sel_hi:[1,1,0]
	v_pk_fma_f32 v[184:185], v[186:187], v[96:97], v[184:185]
	v_cvt_pk_f32_fp8_sdwa v[186:187], v182 src0_sel:WORD_1
	v_pk_fma_f32 v[184:185], v[188:189], v[90:91], v[184:185]
	v_cvt_pk_f32_fp8_e32 v[188:189], v183
	v_pk_fma_f32 v[180:181], v[180:181], v[92:93], v[184:185]
	v_cvt_pk_f32_fp8_e32 v[184:185], v182
	v_cvt_pk_f32_fp8_sdwa v[182:183], v183 src0_sel:WORD_1
	v_pk_fma_f32 v[180:181], v[184:185], v[86:87], v[180:181]
	v_cvt_pk_f32_fp8_e32 v[184:185], v177
	v_pk_fma_f32 v[180:181], v[186:187], v[88:89], v[180:181]
	v_pk_fma_f32 v[180:181], v[188:189], v[82:83], v[180:181]
	v_pk_fma_f32 v[180:181], v[182:183], v[84:85], v[180:181]
	v_cvt_pk_f32_fp8_sdwa v[182:183], v176 src0_sel:WORD_1
	v_add_f32_e32 v186, v180, v181
	v_cvt_pk_f32_fp8_e32 v[180:181], v176
	v_cvt_pk_f32_fp8_sdwa v[176:177], v177 src0_sel:WORD_1
	v_pk_fma_f32 v[180:181], v[180:181], v[94:95], 0 op_sel_hi:[1,1,0]
	v_pk_fma_f32 v[180:181], v[182:183], v[96:97], v[180:181]
	v_cvt_pk_f32_fp8_sdwa v[182:183], v178 src0_sel:WORD_1
	v_pk_fma_f32 v[180:181], v[184:185], v[90:91], v[180:181]
	v_cvt_pk_f32_fp8_e32 v[184:185], v179
	v_pk_fma_f32 v[176:177], v[176:177], v[92:93], v[180:181]
	v_cvt_pk_f32_fp8_e32 v[180:181], v178
	v_cvt_pk_f32_fp8_sdwa v[178:179], v179 src0_sel:WORD_1
	v_pk_fma_f32 v[176:177], v[180:181], v[86:87], v[176:177]
	v_cvt_pk_f32_fp8_e32 v[180:181], v173
	v_pk_fma_f32 v[176:177], v[182:183], v[88:89], v[176:177]
	v_pk_fma_f32 v[176:177], v[184:185], v[82:83], v[176:177]
	v_pk_fma_f32 v[176:177], v[178:179], v[84:85], v[176:177]
	v_cvt_pk_f32_fp8_sdwa v[178:179], v172 src0_sel:WORD_1
	v_add_f32_e32 v182, v176, v177
	v_cvt_pk_f32_fp8_e32 v[176:177], v172
	v_cvt_pk_f32_fp8_sdwa v[172:173], v173 src0_sel:WORD_1
	v_pk_fma_f32 v[176:177], v[176:177], v[94:95], 0 op_sel_hi:[1,1,0]
	v_pk_fma_f32 v[176:177], v[178:179], v[96:97], v[176:177]
	v_cvt_pk_f32_fp8_sdwa v[178:179], v174 src0_sel:WORD_1
	v_pk_fma_f32 v[176:177], v[180:181], v[90:91], v[176:177]
	v_cvt_pk_f32_fp8_e32 v[180:181], v175
	v_pk_fma_f32 v[172:173], v[172:173], v[92:93], v[176:177]
	v_cvt_pk_f32_fp8_e32 v[176:177], v174
	v_cvt_pk_f32_fp8_sdwa v[174:175], v175 src0_sel:WORD_1
	v_pk_fma_f32 v[172:173], v[176:177], v[86:87], v[172:173]
	v_cvt_pk_f32_fp8_e32 v[176:177], v169
	v_pk_fma_f32 v[172:173], v[178:179], v[88:89], v[172:173]
	v_pk_fma_f32 v[172:173], v[180:181], v[82:83], v[172:173]
	v_pk_fma_f32 v[172:173], v[174:175], v[84:85], v[172:173]
	v_cvt_pk_f32_fp8_sdwa v[174:175], v168 src0_sel:WORD_1
	v_add_f32_e32 v178, v172, v173
	v_cvt_pk_f32_fp8_e32 v[172:173], v168
	v_cvt_pk_f32_fp8_sdwa v[168:169], v169 src0_sel:WORD_1
	v_pk_fma_f32 v[172:173], v[172:173], v[94:95], 0 op_sel_hi:[1,1,0]
	v_pk_fma_f32 v[172:173], v[174:175], v[96:97], v[172:173]
	v_cvt_pk_f32_fp8_sdwa v[174:175], v170 src0_sel:WORD_1
	v_pk_fma_f32 v[172:173], v[176:177], v[90:91], v[172:173]
	v_cvt_pk_f32_fp8_e32 v[176:177], v171
	v_pk_fma_f32 v[168:169], v[168:169], v[92:93], v[172:173]
	v_cvt_pk_f32_fp8_e32 v[172:173], v170
	v_cvt_pk_f32_fp8_sdwa v[170:171], v171 src0_sel:WORD_1
	s_waitcnt vmcnt(1)
; __device__ __forceinline__ f32x2 fp8x2_lo(unsigned w) { return __builtin_amdgcn_cvt_pk_f32_fp8(w, false); }
; __device__ __forceinline__ f32x2 fp8x2_hi(unsigned w) { return __builtin_amdgcn_cvt_pk_f32_fp8(w, true); }
; #define PA_IDS(T) do { const unsigned* kp_ = KP + (size_t)(T) * 256; _Pragma("unroll") for (int qq = 0; qq < 4; ++qq) idv[qq] = *(const u32x4*)(kp_ + 4 * qq); } while (0)
; template <bool NT>
; __device__ __forceinline__ void peer_passA(const Args& a, const PeerWork w) {
;     ...
;         u32x4 urn[16]; f32x4 hn[4];
;         PA_GATHER(t1, urn, hn);
;         const int t2 = peer_tok(w, min(q + 2 * qs, ql));
;         PA_IDS(t2);
;         float part[16];
; #pragma unroll
;         for (int k = 0; k < 16; ++k) {
;             const unsigned ww[4] = {ur[k].x, ur[k].y, ur[k].z, ur[k].w};
;             f32x2 p2 = {0.f, 0.f};
; #pragma unroll
;             for (int wd = 0; wd < 4; ++wd) { p2 = __builtin_elementwise_fma(fp8x2_lo(ww[wd]), (f32x2){hv[wd][0], hv[wd][1]}, p2); p2 = __builtin_elementwise_fma(fp8x2_hi(ww[wd]), (f32x2){hv[wd][2], hv[wd][3]}, p2); }
;             part[k] = p2[0] + p2[1];
	v_lshl_or_b32 v10, v30, 7, v1
	v_pk_fma_f32 v[168:169], v[172:173], v[86:87], v[168:169]
	v_cvt_pk_f32_fp8_e32 v[172:173], v165
	v_pk_fma_f32 v[168:169], v[174:175], v[88:89], v[168:169]
	v_lshl_or_b32 v11, v31, 7, v1
	v_pk_fma_f32 v[168:169], v[176:177], v[82:83], v[168:169]
	v_lshl_or_b32 v22, v32, 7, v1
	v_pk_fma_f32 v[168:169], v[170:171], v[84:85], v[168:169]
	v_cvt_pk_f32_fp8_sdwa v[170:171], v164 src0_sel:WORD_1
	v_add_f32_e32 v174, v168, v169
	v_cvt_pk_f32_fp8_e32 v[168:169], v164
	v_cvt_pk_f32_fp8_sdwa v[164:165], v165 src0_sel:WORD_1
	v_lshl_or_b32 v23, v33, 7, v1
	v_lshl_or_b32 v18, v18, 7, v1
	v_pk_fma_f32 v[168:169], v[168:169], v[94:95], 0 op_sel_hi:[1,1,0]
	v_lshl_or_b32 v19, v19, 7, v1
	v_pk_fma_f32 v[168:169], v[170:171], v[96:97], v[168:169]
	v_cvt_pk_f32_fp8_sdwa v[170:171], v166 src0_sel:WORD_1
	v_pk_fma_f32 v[168:169], v[172:173], v[90:91], v[168:169]
	v_cvt_pk_f32_fp8_e32 v[172:173], v167
	v_pk_fma_f32 v[164:165], v[164:165], v[92:93], v[168:169]
	v_cvt_pk_f32_fp8_e32 v[168:169], v166
	v_cvt_pk_f32_fp8_sdwa v[166:167], v167 src0_sel:WORD_1
	global_load_dwordx4 v[2:5], v10, s[10:11]
	global_load_dwordx4 v[6:9], v11, s[10:11]
	v_pk_fma_f32 v[164:165], v[168:169], v[86:87], v[164:165]
	v_cvt_pk_f32_fp8_e32 v[168:169], v161
	v_pk_fma_f32 v[164:165], v[170:171], v[88:89], v[164:165]
	global_load_dwordx4 v[10:13], v22, s[10:11]
	global_load_dwordx4 v[14:17], v23, s[10:11]
	v_pk_fma_f32 v[164:165], v[172:173], v[82:83], v[164:165]
	global_load_dwordx4 v[22:25], v18, s[10:11]
	global_load_dwordx4 v[26:29], v19, s[10:11]
	v_pk_fma_f32 v[164:165], v[166:167], v[84:85], v[164:165]
	v_cvt_pk_f32_fp8_sdwa v[166:167], v160 src0_sel:WORD_1
	v_add_f32_e32 v170, v164, v165
	v_cvt_pk_f32_fp8_e32 v[164:165], v160
	v_cvt_pk_f32_fp8_sdwa v[160:161], v161 src0_sel:WORD_1
	v_lshl_or_b32 v18, v20, 7, v1
	v_lshl_or_b32 v19, v21, 7, v1
	v_pk_fma_f32 v[164:165], v[164:165], v[94:95], 0 op_sel_hi:[1,1,0]
	global_load_dwordx4 v[34:37], v18, s[10:11]
	global_load_dwordx4 v[38:41], v19, s[10:11]
	v_pk_fma_f32 v[164:165], v[166:167], v[96:97], v[164:165]
	v_cvt_pk_f32_fp8_sdwa v[166:167], v162 src0_sel:WORD_1
	v_pk_fma_f32 v[164:165], v[168:169], v[90:91], v[164:165]
	v_cvt_pk_f32_fp8_e32 v[168:169], v163
	v_pk_fma_f32 v[160:161], v[160:161], v[92:93], v[164:165]
	v_cvt_pk_f32_fp8_e32 v[164:165], v162
	v_cvt_pk_f32_fp8_sdwa v[162:163], v163 src0_sel:WORD_1
	v_lshl_or_b32 v18, v62, 7, v1
	v_lshl_or_b32 v19, v63, 7, v1
	v_pk_fma_f32 v[160:161], v[164:165], v[86:87], v[160:161]
	v_cvt_pk_f32_fp8_e32 v[164:165], v151
	v_pk_fma_f32 v[160:161], v[166:167], v[88:89], v[160:161]
	global_load_dwordx4 v[42:45], v18, s[10:11]
	global_load_dwordx4 v[46:49], v19, s[10:11]
	v_pk_fma_f32 v[160:161], v[168:169], v[82:83], v[160:161]
	v_lshl_or_b32 v18, v64, 7, v1
	v_pk_fma_f32 v[160:161], v[162:163], v[84:85], v[160:161]
	v_cvt_pk_f32_fp8_sdwa v[162:163], v150 src0_sel:WORD_1
	v_add_f32_e32 v166, v160, v161
	v_cvt_pk_f32_fp8_e32 v[160:161], v150
	v_cvt_pk_f32_fp8_sdwa v[150:151], v151 src0_sel:WORD_1
	v_lshl_or_b32 v19, v65, 7, v1
	s_mov_b32 s18, s16
	v_pk_fma_f32 v[160:161], v[160:161], v[94:95], 0 op_sel_hi:[1,1,0]
	s_mov_b32 s16, s14
	v_pk_fma_f32 v[160:161], v[162:163], v[96:97], v[160:161]
	v_cvt_pk_f32_fp8_sdwa v[162:163], v152 src0_sel:WORD_1
	v_pk_fma_f32 v[160:161], v[164:165], v[90:91], v[160:161]
	v_cvt_pk_f32_fp8_e32 v[164:165], v153
	v_pk_fma_f32 v[150:151], v[150:151], v[92:93], v[160:161]
	v_cvt_pk_f32_fp8_e32 v[160:161], v152
	v_cvt_pk_f32_fp8_sdwa v[152:153], v153 src0_sel:WORD_1
	global_load_dwordx4 v[54:57], v18, s[10:11]
	global_load_dwordx4 v[58:61], v19, s[10:11]
	v_pk_fma_f32 v[150:151], v[160:161], v[86:87], v[150:151]
	v_cvt_pk_f32_fp8_e32 v[160:161], v147
	v_pk_fma_f32 v[150:151], v[162:163], v[88:89], v[150:151]
	v_lshl_or_b32 v18, v50, 7, v1
	v_pk_fma_f32 v[150:151], v[164:165], v[82:83], v[150:151]
	v_lshl_or_b32 v19, v51, 7, v1
	v_pk_fma_f32 v[150:151], v[152:153], v[84:85], v[150:151]
	v_cvt_pk_f32_fp8_sdwa v[152:153], v146 src0_sel:WORD_1
	v_add_f32_e32 v162, v150, v151
	v_cvt_pk_f32_fp8_e32 v[150:151], v146
	v_cvt_pk_f32_fp8_sdwa v[146:147], v147 src0_sel:WORD_1
	s_ashr_i32 s17, s14, 31
	v_pk_fma_f32 v[150:151], v[150:151], v[94:95], 0 op_sel_hi:[1,1,0]
	v_pk_fma_f32 v[150:151], v[152:153], v[96:97], v[150:151]
	v_cvt_pk_f32_fp8_sdwa v[152:153], v148 src0_sel:WORD_1
	v_pk_fma_f32 v[150:151], v[160:161], v[90:91], v[150:151]
	v_cvt_pk_f32_fp8_e32 v[160:161], v149
	v_pk_fma_f32 v[146:147], v[146:147], v[92:93], v[150:151]
	v_cvt_pk_f32_fp8_e32 v[150:151], v148
	v_cvt_pk_f32_fp8_sdwa v[148:149], v149 src0_sel:WORD_1
	global_load_dwordx4 v[66:69], v18, s[10:11]
	global_load_dwordx4 v[70:73], v19, s[10:11]
	v_pk_fma_f32 v[146:147], v[150:151], v[86:87], v[146:147]
	v_cvt_pk_f32_fp8_e32 v[150:151], v143
	v_pk_fma_f32 v[146:147], v[152:153], v[88:89], v[146:147]
	v_lshl_or_b32 v18, v52, 7, v1
	v_pk_fma_f32 v[146:147], v[160:161], v[82:83], v[146:147]
	v_lshl_or_b32 v19, v53, 7, v1
	v_pk_fma_f32 v[146:147], v[148:149], v[84:85], v[146:147]
	v_cvt_pk_f32_fp8_sdwa v[148:149], v142 src0_sel:WORD_1
	v_add_f32_e32 v152, v146, v147
	v_cvt_pk_f32_fp8_e32 v[146:147], v142
	v_cvt_pk_f32_fp8_sdwa v[142:143], v143 src0_sel:WORD_1
	s_lshl_b64 s[14:15], s[16:17], 12
	s_add_i32 s17, s12, s13
	v_pk_fma_f32 v[146:147], v[146:147], v[94:95], 0 op_sel_hi:[1,1,0]
	v_pk_fma_f32 v[146:147], v[148:149], v[96:97], v[146:147]
	v_cvt_pk_f32_fp8_sdwa v[148:149], v144 src0_sel:WORD_1
	v_pk_fma_f32 v[146:147], v[150:151], v[90:91], v[146:147]
	v_cvt_pk_f32_fp8_e32 v[150:151], v145
	v_pk_fma_f32 v[142:143], v[142:143], v[92:93], v[146:147]
	v_cvt_pk_f32_fp8_e32 v[146:147], v144
; __device__ __forceinline__ f32x2 fp8x2_lo(unsigned w) { return __builtin_amdgcn_cvt_pk_f32_fp8(w, false); }
; __device__ __forceinline__ f32x2 fp8x2_hi(unsigned w) { return __builtin_amdgcn_cvt_pk_f32_fp8(w, true); }
; #define PA_IDS(T) do { const unsigned* kp_ = KP + (size_t)(T) * 256; _Pragma("unroll") for (int qq = 0; qq < 4; ++qq) idv[qq] = *(const u32x4*)(kp_ + 4 * qq); } while (0)
; template <bool NT>
; __device__ __forceinline__ void peer_passA(const Args& a, const PeerWork w) {
;     ...
;     int t = peer_tok(w, q), t1 = peer_tok(w, min(q + qs, ql));
;     PA_IDS(t);
;     PA_GATHER(t, ur, hv);
;     PA_IDS(t1);
; #pragma unroll 1
;     for (;; q += qs) {
;         u32x4 urn[16]; f32x4 hn[4];
;         PA_GATHER(t1, urn, hn);
;         const int t2 = peer_tok(w, min(q + 2 * qs, ql));
;         PA_IDS(t2);
;         float part[16];
; #pragma unroll
;         for (int k = 0; k < 16; ++k) {
;             const unsigned ww[4] = {ur[k].x, ur[k].y, ur[k].z, ur[k].w};
;             f32x2 p2 = {0.f, 0.f};
; #pragma unroll
;             for (int wd = 0; wd < 4; ++wd) { p2 = __builtin_elementwise_fma(fp8x2_lo(ww[wd]), (f32x2){hv[wd][0], hv[wd][1]}, p2); p2 = __builtin_elementwise_fma(fp8x2_hi(ww[wd]), (f32x2){hv[wd][2], hv[wd][3]}, p2); }
	v_cvt_pk_f32_fp8_sdwa v[144:145], v145 src0_sel:WORD_1
	global_load_dwordx4 v[74:77], v18, s[10:11]
	global_load_dwordx4 v[78:81], v19, s[10:11]
	v_pk_fma_f32 v[142:143], v[146:147], v[86:87], v[142:143]
	v_cvt_pk_f32_fp8_e32 v[146:147], v139
	v_pk_fma_f32 v[142:143], v[148:149], v[88:89], v[142:143]
	v_lshl_add_u64 v[18:19], v[156:157], 0, s[14:15]
	v_pk_fma_f32 v[142:143], v[150:151], v[82:83], v[142:143]
	s_min_i32 s14, s17, 0x3fff
	v_pk_fma_f32 v[142:143], v[144:145], v[84:85], v[142:143]
	v_cvt_pk_f32_fp8_sdwa v[144:145], v138 src0_sel:WORD_1
	v_add_f32_e32 v148, v142, v143
	v_cvt_pk_f32_fp8_e32 v[142:143], v138
	v_cvt_pk_f32_fp8_sdwa v[138:139], v139 src0_sel:WORD_1
	s_ashr_i32 s15, s14, 31
	s_lshl_b64 s[28:29], s[14:15], 10
	v_pk_fma_f32 v[142:143], v[142:143], v[94:95], 0 op_sel_hi:[1,1,0]
	v_lshl_add_u64 v[30:31], v[154:155], 0, s[28:29]
	v_pk_fma_f32 v[142:143], v[144:145], v[96:97], v[142:143]
	v_cvt_pk_f32_fp8_sdwa v[144:145], v140 src0_sel:WORD_1
	v_pk_fma_f32 v[142:143], v[146:147], v[90:91], v[142:143]
	v_cvt_pk_f32_fp8_e32 v[146:147], v141
	v_pk_fma_f32 v[138:139], v[138:139], v[92:93], v[142:143]
	v_cvt_pk_f32_fp8_e32 v[142:143], v140
	v_cvt_pk_f32_fp8_sdwa v[140:141], v141 src0_sel:WORD_1
	global_load_dwordx4 v[110:113], v[18:19], off offset:48
	global_load_dwordx4 v[106:109], v[18:19], off offset:32
	global_load_dwordx4 v[102:105], v[18:19], off offset:16
	global_load_dwordx4 v[98:101], v[18:19], off
	global_load_dwordx4 v[50:53], v[30:31], off offset:48
	global_load_dwordx4 v[62:65], v[30:31], off offset:32
	s_nop 0
	global_load_dwordx4 v[18:21], v[30:31], off offset:16
	s_nop 0
	global_load_dwordx4 v[30:33], v[30:31], off
	v_pk_fma_f32 v[138:139], v[142:143], v[86:87], v[138:139]
	v_cvt_pk_f32_fp8_e32 v[142:143], v135
	v_pk_fma_f32 v[138:139], v[144:145], v[88:89], v[138:139]
	s_ashr_i32 s19, s18, 31
	v_pk_fma_f32 v[138:139], v[146:147], v[82:83], v[138:139]
	s_lshl_b64 s[18:19], s[18:19], 11
	v_pk_fma_f32 v[138:139], v[140:141], v[84:85], v[138:139]
	v_cvt_pk_f32_fp8_sdwa v[140:141], v134 src0_sel:WORD_1
	v_add_f32_e32 v144, v138, v139
	v_cvt_pk_f32_fp8_e32 v[138:139], v134
	v_cvt_pk_f32_fp8_sdwa v[134:135], v135 src0_sel:WORD_1
	s_add_i32 s12, s22, s12
	s_cmpk_gt_i32 s12, 0x3fff
	v_pk_fma_f32 v[138:139], v[138:139], v[94:95], 0 op_sel_hi:[1,1,0]
	v_readfirstlane_b32 s12, v0
	v_pk_fma_f32 v[138:139], v[140:141], v[96:97], v[138:139]
	v_cvt_pk_f32_fp8_sdwa v[140:141], v136 src0_sel:WORD_1
	v_pk_fma_f32 v[138:139], v[142:143], v[90:91], v[138:139]
	v_cvt_pk_f32_fp8_e32 v[142:143], v137
	v_pk_fma_f32 v[134:135], v[134:135], v[92:93], v[138:139]
	v_cvt_pk_f32_fp8_e32 v[138:139], v136
	v_cvt_pk_f32_fp8_sdwa v[136:137], v137 src0_sel:WORD_1
	v_pk_fma_f32 v[134:135], v[138:139], v[86:87], v[134:135]
	s_nop 0
	v_pk_fma_f32 v[134:135], v[140:141], v[88:89], v[134:135]
	v_cvt_pk_f32_fp8_e32 v[138:139], v131
	v_pk_fma_f32 v[134:135], v[142:143], v[82:83], v[134:135]
	s_nop 0
	v_pk_fma_f32 v[134:135], v[136:137], v[84:85], v[134:135]
	v_cvt_pk_f32_fp8_sdwa v[136:137], v130 src0_sel:WORD_1
	v_add_f32_e32 v140, v134, v135
	v_cvt_pk_f32_fp8_e32 v[134:135], v130
	v_cvt_pk_f32_fp8_sdwa v[130:131], v131 src0_sel:WORD_1
	v_pk_fma_f32 v[134:135], v[134:135], v[94:95], 0 op_sel_hi:[1,1,0]
	s_nop 0
	v_pk_fma_f32 v[134:135], v[136:137], v[96:97], v[134:135]
	v_cvt_pk_f32_fp8_sdwa v[136:137], v132 src0_sel:WORD_1
	v_pk_fma_f32 v[134:135], v[138:139], v[90:91], v[134:135]
	v_cvt_pk_f32_fp8_e32 v[138:139], v133
	v_pk_fma_f32 v[130:131], v[130:131], v[92:93], v[134:135]
	v_cvt_pk_f32_fp8_e32 v[134:135], v132
	v_cvt_pk_f32_fp8_sdwa v[132:133], v133 src0_sel:WORD_1
	v_pk_fma_f32 v[130:131], v[134:135], v[86:87], v[130:131]
	s_nop 0
	v_pk_fma_f32 v[130:131], v[136:137], v[88:89], v[130:131]
	v_cvt_pk_f32_fp8_e32 v[134:135], v127
	v_pk_fma_f32 v[130:131], v[138:139], v[82:83], v[130:131]
	s_nop 0
	v_pk_fma_f32 v[130:131], v[132:133], v[84:85], v[130:131]
	v_cvt_pk_f32_fp8_sdwa v[132:133], v126 src0_sel:WORD_1
	v_add_f32_e32 v136, v130, v131
	v_cvt_pk_f32_fp8_e32 v[130:131], v126
	v_cvt_pk_f32_fp8_sdwa v[126:127], v127 src0_sel:WORD_1
	v_pk_fma_f32 v[130:131], v[130:131], v[94:95], 0 op_sel_hi:[1,1,0]
	s_nop 0
	v_pk_fma_f32 v[130:131], v[132:133], v[96:97], v[130:131]
	v_cvt_pk_f32_fp8_sdwa v[132:133], v128 src0_sel:WORD_1
	v_pk_fma_f32 v[130:131], v[134:135], v[90:91], v[130:131]
	v_cvt_pk_f32_fp8_e32 v[134:135], v129
	v_pk_fma_f32 v[126:127], v[126:127], v[92:93], v[130:131]
	v_cvt_pk_f32_fp8_e32 v[130:131], v128
	v_cvt_pk_f32_fp8_sdwa v[128:129], v129 src0_sel:WORD_1
	v_pk_fma_f32 v[126:127], v[130:131], v[86:87], v[126:127]
	s_nop 0
	v_pk_fma_f32 v[126:127], v[132:133], v[88:89], v[126:127]
	v_cvt_pk_f32_fp8_e32 v[130:131], v123
	v_pk_fma_f32 v[126:127], v[134:135], v[82:83], v[126:127]
	s_nop 0
	v_pk_fma_f32 v[126:127], v[128:129], v[84:85], v[126:127]
	v_cvt_pk_f32_fp8_sdwa v[128:129], v122 src0_sel:WORD_1
	v_add_f32_e32 v132, v126, v127
	v_cvt_pk_f32_fp8_e32 v[126:127], v122
	v_cvt_pk_f32_fp8_sdwa v[122:123], v123 src0_sel:WORD_1
	v_pk_fma_f32 v[126:127], v[126:127], v[94:95], 0 op_sel_hi:[1,1,0]
	s_nop 0
	v_pk_fma_f32 v[126:127], v[128:129], v[96:97], v[126:127]
	v_cvt_pk_f32_fp8_sdwa v[128:129], v124 src0_sel:WORD_1
	v_pk_fma_f32 v[126:127], v[130:131], v[90:91], v[126:127]
	v_cvt_pk_f32_fp8_e32 v[130:131], v125
	v_pk_fma_f32 v[122:123], v[122:123], v[92:93], v[126:127]
	v_cvt_pk_f32_fp8_e32 v[126:127], v124
	v_cvt_pk_f32_fp8_sdwa v[124:125], v125 src0_sel:WORD_1
	v_pk_fma_f32 v[122:123], v[126:127], v[86:87], v[122:123]
	s_nop 0
	v_pk_fma_f32 v[122:123], v[128:129], v[88:89], v[122:123]
	v_cvt_pk_f32_fp8_e32 v[126:127], v119
; __device__ __forceinline__ unsigned cvt_pk_bf16(float lo, float hi) { unsigned r; asm volatile("v_cvt_pk_bf16_f32 %0, %1, %2" : "=v"(r) : "v"(lo), "v"(hi)); return r; }
; template <int CTRL> __device__ __forceinline__ float dpp_f(float x) { return __uint_as_float((unsigned)__builtin_amdgcn_update_dpp(0, (int)__float_as_uint(x), CTRL, 0xf, 0xf, false)); }
; __device__ __forceinline__ f32x2 fp8x2_lo(unsigned w) { return __builtin_amdgcn_cvt_pk_f32_fp8(w, false); }
; __device__ __forceinline__ f32x2 fp8x2_hi(unsigned w) { return __builtin_amdgcn_cvt_pk_f32_fp8(w, true); }
; __device__ __forceinline__ float xor4_f(float x) { float r = dpp_bank_f<0x104, 0x5>(0.f, x); return dpp_bank_f<0x114, 0xa>(r, x); }
; template <bool NT>
; __device__ __forceinline__ void peer_passA(const Args& a, const PeerWork w) {
;     ...
;             for (int wd = 0; wd < 4; ++wd) { p2 = __builtin_elementwise_fma(fp8x2_lo(ww[wd]), (f32x2){hv[wd][0], hv[wd][1]}, p2); p2 = __builtin_elementwise_fma(fp8x2_hi(ww[wd]), (f32x2){hv[wd][2], hv[wd][3]}, p2); }
;             part[k] = p2[0] + p2[1];
;         }
;         float w8[8], w4[4], w2[2];
;         { const bool up = (lane & 4) != 0;
; #pragma unroll
;           for (int m = 0; m < 8; ++m) { const float keep = up ? part[m + 8] : part[m], send = up ? part[m] : part[m + 8]; w8[m] = keep + xor4_f(send); } }
;         { const bool up = (lane & 2) != 0;
; #pragma unroll
;           for (int m = 0; m < 4; ++m) { const float keep = up ? w8[m + 4] : w8[m], send = up ? w8[m] : w8[m + 4]; w4[m] = keep + dpp_f<0x4E>(send); } }
;         { const bool up = (lane & 1) != 0;
; #pragma unroll
;           for (int m = 0; m < 2; ++m) { const float keep = up ? w4[m + 2] : w4[m], send = up ? w4[m] : w4[m + 2]; w2[m] = keep + dpp_f<0xB1>(send); } }
;         PD[(size_t)t * 512] = cvt_pk_bf16(w2[0], w2[1]);
;         if (q + qs > ql) break;
	v_pk_fma_f32 v[122:123], v[130:131], v[82:83], v[122:123]
	s_nop 0
	v_pk_fma_f32 v[122:123], v[124:125], v[84:85], v[122:123]
	v_cvt_pk_f32_fp8_sdwa v[124:125], v118 src0_sel:WORD_1
	v_add_f32_e32 v128, v122, v123
	v_cvt_pk_f32_fp8_e32 v[122:123], v118
	v_cvt_pk_f32_fp8_sdwa v[118:119], v119 src0_sel:WORD_1
	v_pk_fma_f32 v[122:123], v[122:123], v[94:95], 0 op_sel_hi:[1,1,0]
	s_nop 0
	v_pk_fma_f32 v[122:123], v[124:125], v[96:97], v[122:123]
	v_cvt_pk_f32_fp8_sdwa v[124:125], v120 src0_sel:WORD_1
	v_pk_fma_f32 v[122:123], v[126:127], v[90:91], v[122:123]
	v_cvt_pk_f32_fp8_e32 v[126:127], v121
	v_pk_fma_f32 v[118:119], v[118:119], v[92:93], v[122:123]
	v_cvt_pk_f32_fp8_e32 v[122:123], v120
	v_cvt_pk_f32_fp8_sdwa v[120:121], v121 src0_sel:WORD_1
	v_pk_fma_f32 v[118:119], v[122:123], v[86:87], v[118:119]
	s_nop 0
	v_pk_fma_f32 v[118:119], v[124:125], v[88:89], v[118:119]
	v_cvt_pk_f32_fp8_e32 v[122:123], v115
	v_pk_fma_f32 v[118:119], v[126:127], v[82:83], v[118:119]
	s_nop 0
	v_pk_fma_f32 v[118:119], v[120:121], v[84:85], v[118:119]
	v_cvt_pk_f32_fp8_sdwa v[120:121], v114 src0_sel:WORD_1
	v_add_f32_e32 v124, v118, v119
	v_cvt_pk_f32_fp8_e32 v[118:119], v114
	v_cvt_pk_f32_fp8_sdwa v[114:115], v115 src0_sel:WORD_1
	v_pk_fma_f32 v[94:95], v[118:119], v[94:95], 0 op_sel_hi:[1,1,0]
	s_nop 0
	v_pk_fma_f32 v[94:95], v[120:121], v[96:97], v[94:95]
	v_cvt_pk_f32_fp8_e32 v[96:97], v117
	v_pk_fma_f32 v[90:91], v[122:123], v[90:91], v[94:95]
	v_cvt_pk_f32_fp8_sdwa v[94:95], v116 src0_sel:WORD_1
	v_pk_fma_f32 v[90:91], v[114:115], v[92:93], v[90:91]
	v_cvt_pk_f32_fp8_e32 v[92:93], v116
	v_cvt_pk_f32_fp8_sdwa v[114:115], v117 src0_sel:WORD_1
	v_pk_fma_f32 v[86:87], v[92:93], v[86:87], v[90:91]
	s_nop 0
	v_pk_fma_f32 v[86:87], v[94:95], v[88:89], v[86:87]
	v_pk_fma_f32 v[82:83], v[96:97], v[82:83], v[86:87]
	v_pk_fma_f32 v[82:83], v[114:115], v[84:85], v[82:83]
	v_cndmask_b32_e64 v84, v186, v148, s[0:1]
	v_add_f32_e32 v82, v82, v83
	v_cndmask_b32_e64 v83, v148, v186, s[0:1]
	s_nop 0
	v_add_f32_dpp v83, v84, v83 row_half_mirror row_mask:0xf bank_mask:0xf bound_ctrl:1
	v_cndmask_b32_e64 v85, v182, v144, s[0:1]
	v_cndmask_b32_e64 v84, v144, v182, s[0:1]
	s_nop 0
	v_add_f32_dpp v84, v85, v84 row_half_mirror row_mask:0xf bank_mask:0xf bound_ctrl:1
	v_cndmask_b32_e64 v86, v178, v140, s[0:1]
	v_cndmask_b32_e64 v85, v140, v178, s[0:1]
	s_nop 0
	s_nop 0
	v_add_f32_dpp v85, v86, v85 row_half_mirror row_mask:0xf bank_mask:0xf bound_ctrl:1
	v_cndmask_b32_e64 v87, v174, v136, s[0:1]
	v_cndmask_b32_e64 v86, v136, v174, s[0:1]
	s_nop 0
	s_nop 0
	v_add_f32_dpp v86, v87, v86 row_half_mirror row_mask:0xf bank_mask:0xf bound_ctrl:1
	v_cndmask_b32_e64 v88, v170, v132, s[0:1]
	v_cndmask_b32_e64 v87, v132, v170, s[0:1]
	s_nop 0
	s_nop 0
	v_add_f32_dpp v87, v88, v87 row_half_mirror row_mask:0xf bank_mask:0xf bound_ctrl:1
	v_cndmask_b32_e64 v89, v166, v128, s[0:1]
	v_cndmask_b32_e64 v88, v128, v166, s[0:1]
	s_nop 0
	s_nop 0
	v_add_f32_dpp v88, v89, v88 row_half_mirror row_mask:0xf bank_mask:0xf bound_ctrl:1
	v_cndmask_b32_e64 v90, v162, v124, s[0:1]
	v_cndmask_b32_e64 v89, v124, v162, s[0:1]
	s_nop 0
	s_nop 0
	v_add_f32_dpp v89, v90, v89 row_half_mirror row_mask:0xf bank_mask:0xf bound_ctrl:1
	v_cndmask_b32_e64 v90, v82, v152, s[0:1]
	v_cndmask_b32_e64 v82, v152, v82, s[0:1]
	v_mov_b32_e32 v91, 0
	s_nop 1
	s_nop 0
	v_add_f32_dpp v82, v82, v90 row_half_mirror row_mask:0xf bank_mask:0xf bound_ctrl:1
	v_cndmask_b32_e64 v90, v87, v83, s[4:5]
	v_cndmask_b32_e64 v83, v83, v87, s[4:5]
	v_cndmask_b32_e64 v87, v88, v84, s[4:5]
	v_cndmask_b32_e64 v84, v84, v88, s[4:5]
	v_add_f32_dpp v83, v83, v90 quad_perm:[2,3,0,1] row_mask:0xf bank_mask:0xf bound_ctrl:1
	s_nop 0
	v_add_f32_dpp v84, v84, v87 quad_perm:[2,3,0,1] row_mask:0xf bank_mask:0xf bound_ctrl:1
	v_cndmask_b32_e64 v87, v89, v85, s[4:5]
	v_cndmask_b32_e64 v85, v85, v89, s[4:5]
	s_nop 1
	v_add_f32_dpp v85, v85, v87 quad_perm:[2,3,0,1] row_mask:0xf bank_mask:0xf bound_ctrl:1
	v_cndmask_b32_e64 v87, v82, v86, s[4:5]
	v_cndmask_b32_e64 v82, v86, v82, s[4:5]
	v_cndmask_b32_e64 v86, v85, v83, s[6:7]
	v_cndmask_b32_e64 v83, v83, v85, s[6:7]
	v_add_f32_dpp v82, v82, v87 quad_perm:[2,3,0,1] row_mask:0xf bank_mask:0xf bound_ctrl:1
	v_cndmask_b32_e64 v85, v82, v84, s[6:7]
	v_cndmask_b32_e64 v82, v84, v82, s[6:7]
	v_add_f32_dpp v83, v83, v86 quad_perm:[1,0,3,2] row_mask:0xf bank_mask:0xf bound_ctrl:1
	s_nop 0
	v_add_f32_dpp v82, v82, v85 quad_perm:[1,0,3,2] row_mask:0xf bank_mask:0xf bound_ctrl:1
	v_cvt_pk_bf16_f32 v84, v83, v82
	v_lshl_add_u64 v[82:83], v[158:159], 0, s[18:19]
	s_mov_b64 s[18:19], -1
	global_store_dword v[82:83], v84, off
	s_cbranch_scc1 .LBB0_1323
; __device__ __forceinline__ f32x2 fp8x2_lo(unsigned w) { return __builtin_amdgcn_cvt_pk_f32_fp8(w, false); }
; __device__ __forceinline__ f32x2 fp8x2_hi(unsigned w) { return __builtin_amdgcn_cvt_pk_f32_fp8(w, true); }
; #define PA_IDS(T) do { const unsigned* kp_ = KP + (size_t)(T) * 256; _Pragma("unroll") for (int qq = 0; qq < 4; ++qq) idv[qq] = *(const u32x4*)(kp_ + 4 * qq); } while (0)
; template <bool NT>
; __device__ __forceinline__ void peer_passA(const Args& a, const PeerWork w) {
;     ...
;     for (;; q += qs) {
;         u32x4 urn[16]; f32x4 hn[4];
;         PA_GATHER(t1, urn, hn);
;         const int t2 = peer_tok(w, min(q + 2 * qs, ql));
;         PA_IDS(t2);
;         float part[16];
; #pragma unroll
;         for (int k = 0; k < 16; ++k) {
;             const unsigned ww[4] = {ur[k].x, ur[k].y, ur[k].z, ur[k].w};
;             f32x2 p2 = {0.f, 0.f};
; #pragma unroll
;             for (int wd = 0; wd < 4; ++wd) { p2 = __builtin_elementwise_fma(fp8x2_lo(ww[wd]), (f32x2){hv[wd][0], hv[wd][1]}, p2); p2 = __builtin_elementwise_fma(fp8x2_hi(ww[wd]), (f32x2){hv[wd][2], hv[wd][3]}, p2); }
	s_sub_i32 s12, s17, s22
	s_mov_b64 s[18:19], 0
	s_waitcnt vmcnt(24)
	v_cvt_pk_f32_fp8_e32 v[184:185], v2
	v_cvt_pk_f32_fp8_sdwa v[186:187], v2 src0_sel:WORD_1
	v_cvt_pk_f32_fp8_e32 v[188:189], v3
	v_cvt_pk_f32_fp8_sdwa v[2:3], v3 src0_sel:WORD_1
	s_waitcnt vmcnt(5)
	v_pk_fma_f32 v[184:185], v[184:185], v[98:99], 0 op_sel_hi:[1,1,0]
	v_pk_fma_f32 v[184:185], v[186:187], v[100:101], v[184:185]
	v_cvt_pk_f32_fp8_sdwa v[186:187], v4 src0_sel:WORD_1
	v_pk_fma_f32 v[184:185], v[188:189], v[102:103], v[184:185]
	v_cvt_pk_f32_fp8_e32 v[188:189], v5
	v_pk_fma_f32 v[2:3], v[2:3], v[104:105], v[184:185]
	v_cvt_pk_f32_fp8_e32 v[184:185], v4
	v_cvt_pk_f32_fp8_sdwa v[4:5], v5 src0_sel:WORD_1
	v_pk_fma_f32 v[2:3], v[184:185], v[106:107], v[2:3]
	v_cvt_pk_f32_fp8_e32 v[184:185], v7
	v_pk_fma_f32 v[2:3], v[186:187], v[108:109], v[2:3]
	v_pk_fma_f32 v[2:3], v[188:189], v[110:111], v[2:3]
	v_pk_fma_f32 v[2:3], v[4:5], v[112:113], v[2:3]
	v_cvt_pk_f32_fp8_sdwa v[4:5], v6 src0_sel:WORD_1
	v_add_f32_e32 v186, v2, v3
	v_cvt_pk_f32_fp8_e32 v[2:3], v6
	v_cvt_pk_f32_fp8_sdwa v[6:7], v7 src0_sel:WORD_1
	v_pk_fma_f32 v[2:3], v[2:3], v[98:99], 0 op_sel_hi:[1,1,0]
	v_pk_fma_f32 v[2:3], v[4:5], v[100:101], v[2:3]
	v_cvt_pk_f32_fp8_sdwa v[4:5], v8 src0_sel:WORD_1
	v_pk_fma_f32 v[2:3], v[184:185], v[102:103], v[2:3]
	v_cvt_pk_f32_fp8_e32 v[184:185], v9
	v_pk_fma_f32 v[6:7], v[6:7], v[104:105], v[2:3]
	v_cvt_pk_f32_fp8_e32 v[2:3], v8
	v_cvt_pk_f32_fp8_sdwa v[8:9], v9 src0_sel:WORD_1
	v_pk_fma_f32 v[6:7], v[2:3], v[106:107], v[6:7]
	v_cvt_pk_f32_fp8_e32 v[2:3], v11
	v_pk_fma_f32 v[6:7], v[4:5], v[108:109], v[6:7]
	v_pk_fma_f32 v[6:7], v[184:185], v[110:111], v[6:7]
	v_pk_fma_f32 v[6:7], v[8:9], v[112:113], v[6:7]
	v_cvt_pk_f32_fp8_sdwa v[8:9], v10 src0_sel:WORD_1
	v_add_f32_e32 v4, v6, v7
	v_cvt_pk_f32_fp8_e32 v[6:7], v10
	v_cvt_pk_f32_fp8_sdwa v[10:11], v11 src0_sel:WORD_1
	v_pk_fma_f32 v[6:7], v[6:7], v[98:99], 0 op_sel_hi:[1,1,0]
	v_pk_fma_f32 v[6:7], v[8:9], v[100:101], v[6:7]
	v_cvt_pk_f32_fp8_sdwa v[8:9], v12 src0_sel:WORD_1
	v_pk_fma_f32 v[6:7], v[2:3], v[102:103], v[6:7]
	v_cvt_pk_f32_fp8_e32 v[2:3], v13
	v_pk_fma_f32 v[10:11], v[10:11], v[104:105], v[6:7]
	v_cvt_pk_f32_fp8_e32 v[6:7], v12
	v_cvt_pk_f32_fp8_sdwa v[12:13], v13 src0_sel:WORD_1
	v_pk_fma_f32 v[10:11], v[6:7], v[106:107], v[10:11]
	v_cvt_pk_f32_fp8_e32 v[6:7], v15
	v_pk_fma_f32 v[10:11], v[8:9], v[108:109], v[10:11]
	v_pk_fma_f32 v[10:11], v[2:3], v[110:111], v[10:11]
	v_pk_fma_f32 v[10:11], v[12:13], v[112:113], v[10:11]
	v_cvt_pk_f32_fp8_sdwa v[12:13], v14 src0_sel:WORD_1
	v_add_f32_e32 v8, v10, v11
	v_cvt_pk_f32_fp8_e32 v[10:11], v14
	v_cvt_pk_f32_fp8_sdwa v[14:15], v15 src0_sel:WORD_1
	v_pk_fma_f32 v[10:11], v[10:11], v[98:99], 0 op_sel_hi:[1,1,0]
	v_pk_fma_f32 v[10:11], v[12:13], v[100:101], v[10:11]
	v_cvt_pk_f32_fp8_sdwa v[12:13], v16 src0_sel:WORD_1
	v_pk_fma_f32 v[10:11], v[6:7], v[102:103], v[10:11]
	v_cvt_pk_f32_fp8_e32 v[6:7], v17
	v_pk_fma_f32 v[14:15], v[14:15], v[104:105], v[10:11]
	v_cvt_pk_f32_fp8_e32 v[10:11], v16
	v_cvt_pk_f32_fp8_sdwa v[16:17], v17 src0_sel:WORD_1
	s_waitcnt vmcnt(1)
	v_lshl_or_b32 v172, v30, 7, v1
	v_pk_fma_f32 v[14:15], v[10:11], v[106:107], v[14:15]
	v_cvt_pk_f32_fp8_e32 v[10:11], v23
	v_pk_fma_f32 v[14:15], v[12:13], v[108:109], v[14:15]
	v_lshl_or_b32 v173, v31, 7, v1
	v_pk_fma_f32 v[14:15], v[6:7], v[110:111], v[14:15]
	v_lshl_or_b32 v164, v32, 7, v1
	v_pk_fma_f32 v[14:15], v[16:17], v[112:113], v[14:15]
	v_cvt_pk_f32_fp8_sdwa v[16:17], v22 src0_sel:WORD_1
	v_add_f32_e32 v12, v14, v15
	v_cvt_pk_f32_fp8_e32 v[14:15], v22
	v_cvt_pk_f32_fp8_sdwa v[22:23], v23 src0_sel:WORD_1
	v_lshl_or_b32 v165, v33, 7, v1
	v_lshl_or_b32 v18, v18, 7, v1
	v_pk_fma_f32 v[14:15], v[14:15], v[98:99], 0 op_sel_hi:[1,1,0]
	v_lshl_or_b32 v19, v19, 7, v1
	v_pk_fma_f32 v[14:15], v[16:17], v[100:101], v[14:15]
	v_cvt_pk_f32_fp8_sdwa v[16:17], v24 src0_sel:WORD_1
	v_pk_fma_f32 v[14:15], v[10:11], v[102:103], v[14:15]
	v_cvt_pk_f32_fp8_e32 v[10:11], v25
	v_pk_fma_f32 v[22:23], v[22:23], v[104:105], v[14:15]
	v_cvt_pk_f32_fp8_e32 v[14:15], v24
	v_cvt_pk_f32_fp8_sdwa v[24:25], v25 src0_sel:WORD_1
	global_load_dwordx4 v[180:183], v172, s[10:11]
	global_load_dwordx4 v[176:179], v173, s[10:11]
	v_pk_fma_f32 v[22:23], v[14:15], v[106:107], v[22:23]
	v_cvt_pk_f32_fp8_e32 v[14:15], v27
	v_pk_fma_f32 v[22:23], v[16:17], v[108:109], v[22:23]
	global_load_dwordx4 v[172:175], v164, s[10:11]
	global_load_dwordx4 v[168:171], v165, s[10:11]
	v_pk_fma_f32 v[22:23], v[10:11], v[110:111], v[22:23]
	global_load_dwordx4 v[164:167], v18, s[10:11]
	global_load_dwordx4 v[160:163], v19, s[10:11]
	v_pk_fma_f32 v[22:23], v[24:25], v[112:113], v[22:23]
	v_cvt_pk_f32_fp8_sdwa v[24:25], v26 src0_sel:WORD_1
	v_add_f32_e32 v16, v22, v23
	v_cvt_pk_f32_fp8_e32 v[22:23], v26
	v_cvt_pk_f32_fp8_sdwa v[26:27], v27 src0_sel:WORD_1
	v_lshl_or_b32 v18, v20, 7, v1
	v_lshl_or_b32 v19, v21, 7, v1
	v_pk_fma_f32 v[22:23], v[22:23], v[98:99], 0 op_sel_hi:[1,1,0]
	global_load_dwordx4 v[150:153], v18, s[10:11]
	global_load_dwordx4 v[146:149], v19, s[10:11]
	v_pk_fma_f32 v[22:23], v[24:25], v[100:101], v[22:23]
	v_cvt_pk_f32_fp8_sdwa v[24:25], v28 src0_sel:WORD_1
	v_pk_fma_f32 v[22:23], v[14:15], v[102:103], v[22:23]
	v_cvt_pk_f32_fp8_e32 v[14:15], v29
	v_pk_fma_f32 v[26:27], v[26:27], v[104:105], v[22:23]
	v_cvt_pk_f32_fp8_e32 v[22:23], v28
	v_cvt_pk_f32_fp8_sdwa v[28:29], v29 src0_sel:WORD_1
	v_lshl_or_b32 v18, v62, 7, v1
	v_lshl_or_b32 v19, v63, 7, v1
	v_pk_fma_f32 v[26:27], v[22:23], v[106:107], v[26:27]
	v_cvt_pk_f32_fp8_e32 v[22:23], v35
	v_pk_fma_f32 v[26:27], v[24:25], v[108:109], v[26:27]
	global_load_dwordx4 v[142:145], v18, s[10:11]
; __device__ __forceinline__ f32x2 fp8x2_lo(unsigned w) { return __builtin_amdgcn_cvt_pk_f32_fp8(w, false); }
; __device__ __forceinline__ f32x2 fp8x2_hi(unsigned w) { return __builtin_amdgcn_cvt_pk_f32_fp8(w, true); }
; #define PA_IDS(T) do { const unsigned* kp_ = KP + (size_t)(T) * 256; _Pragma("unroll") for (int qq = 0; qq < 4; ++qq) idv[qq] = *(const u32x4*)(kp_ + 4 * qq); } while (0)
; template <bool NT>
; __device__ __forceinline__ void peer_passA(const Args& a, const PeerWork w) {
;     ...
;     int t = peer_tok(w, q), t1 = peer_tok(w, min(q + qs, ql));
;     PA_IDS(t);
;     PA_GATHER(t, ur, hv);
;     PA_IDS(t1);
; #pragma unroll 1
;     for (;; q += qs) {
;         u32x4 urn[16]; f32x4 hn[4];
;         PA_GATHER(t1, urn, hn);
;         const int t2 = peer_tok(w, min(q + 2 * qs, ql));
;         PA_IDS(t2);
;         float part[16];
; #pragma unroll
;         for (int k = 0; k < 16; ++k) {
;             const unsigned ww[4] = {ur[k].x, ur[k].y, ur[k].z, ur[k].w};
;             f32x2 p2 = {0.f, 0.f};
; #pragma unroll
;             for (int wd = 0; wd < 4; ++wd) { p2 = __builtin_elementwise_fma(fp8x2_lo(ww[wd]), (f32x2){hv[wd][0], hv[wd][1]}, p2); p2 = __builtin_elementwise_fma(fp8x2_hi(ww[wd]), (f32x2){hv[wd][2], hv[wd][3]}, p2); }
	global_load_dwordx4 v[138:141], v19, s[10:11]
	v_pk_fma_f32 v[26:27], v[14:15], v[110:111], v[26:27]
	v_lshl_or_b32 v18, v64, 7, v1
	v_pk_fma_f32 v[26:27], v[28:29], v[112:113], v[26:27]
	v_cvt_pk_f32_fp8_sdwa v[28:29], v34 src0_sel:WORD_1
	v_add_f32_e32 v24, v26, v27
	v_cvt_pk_f32_fp8_e32 v[26:27], v34
	v_cvt_pk_f32_fp8_sdwa v[34:35], v35 src0_sel:WORD_1
	v_lshl_or_b32 v19, v65, 7, v1
	s_mov_b32 s18, s16
	v_pk_fma_f32 v[26:27], v[26:27], v[98:99], 0 op_sel_hi:[1,1,0]
	s_mov_b32 s16, s14
	v_pk_fma_f32 v[26:27], v[28:29], v[100:101], v[26:27]
	v_cvt_pk_f32_fp8_sdwa v[28:29], v36 src0_sel:WORD_1
	v_pk_fma_f32 v[26:27], v[22:23], v[102:103], v[26:27]
	v_cvt_pk_f32_fp8_e32 v[22:23], v37
	v_pk_fma_f32 v[34:35], v[34:35], v[104:105], v[26:27]
	v_cvt_pk_f32_fp8_e32 v[26:27], v36
	v_cvt_pk_f32_fp8_sdwa v[36:37], v37 src0_sel:WORD_1
	global_load_dwordx4 v[134:137], v18, s[10:11]
	global_load_dwordx4 v[130:133], v19, s[10:11]
	v_pk_fma_f32 v[34:35], v[26:27], v[106:107], v[34:35]
	v_cvt_pk_f32_fp8_e32 v[26:27], v39
	v_pk_fma_f32 v[34:35], v[28:29], v[108:109], v[34:35]
	v_lshl_or_b32 v18, v50, 7, v1
	v_pk_fma_f32 v[34:35], v[22:23], v[110:111], v[34:35]
	v_lshl_or_b32 v19, v51, 7, v1
	v_pk_fma_f32 v[34:35], v[36:37], v[112:113], v[34:35]
	v_cvt_pk_f32_fp8_sdwa v[36:37], v38 src0_sel:WORD_1
	v_add_f32_e32 v28, v34, v35
	v_cvt_pk_f32_fp8_e32 v[34:35], v38
	v_cvt_pk_f32_fp8_sdwa v[38:39], v39 src0_sel:WORD_1
	s_ashr_i32 s17, s14, 31
	v_pk_fma_f32 v[34:35], v[34:35], v[98:99], 0 op_sel_hi:[1,1,0]
	v_pk_fma_f32 v[34:35], v[36:37], v[100:101], v[34:35]
	v_cvt_pk_f32_fp8_sdwa v[36:37], v40 src0_sel:WORD_1
	v_pk_fma_f32 v[34:35], v[26:27], v[102:103], v[34:35]
	v_cvt_pk_f32_fp8_e32 v[26:27], v41
	v_pk_fma_f32 v[38:39], v[38:39], v[104:105], v[34:35]
	v_cvt_pk_f32_fp8_e32 v[34:35], v40
	v_cvt_pk_f32_fp8_sdwa v[40:41], v41 src0_sel:WORD_1
	global_load_dwordx4 v[126:129], v18, s[10:11]
	global_load_dwordx4 v[122:125], v19, s[10:11]
	v_pk_fma_f32 v[38:39], v[34:35], v[106:107], v[38:39]
	v_cvt_pk_f32_fp8_e32 v[34:35], v43
	v_pk_fma_f32 v[38:39], v[36:37], v[108:109], v[38:39]
	v_lshl_or_b32 v18, v52, 7, v1
	v_pk_fma_f32 v[38:39], v[26:27], v[110:111], v[38:39]
	v_lshl_or_b32 v19, v53, 7, v1
	v_pk_fma_f32 v[38:39], v[40:41], v[112:113], v[38:39]
	v_cvt_pk_f32_fp8_sdwa v[40:41], v42 src0_sel:WORD_1
	v_add_f32_e32 v36, v38, v39
	v_cvt_pk_f32_fp8_e32 v[38:39], v42
	v_cvt_pk_f32_fp8_sdwa v[42:43], v43 src0_sel:WORD_1
	s_lshl_b64 s[14:15], s[16:17], 12
	s_add_i32 s17, s12, s13
	v_pk_fma_f32 v[38:39], v[38:39], v[98:99], 0 op_sel_hi:[1,1,0]
	v_pk_fma_f32 v[38:39], v[40:41], v[100:101], v[38:39]
	v_cvt_pk_f32_fp8_sdwa v[40:41], v44 src0_sel:WORD_1
	v_pk_fma_f32 v[38:39], v[34:35], v[102:103], v[38:39]
	v_cvt_pk_f32_fp8_e32 v[34:35], v45
	v_pk_fma_f32 v[42:43], v[42:43], v[104:105], v[38:39]
	v_cvt_pk_f32_fp8_e32 v[38:39], v44
	v_cvt_pk_f32_fp8_sdwa v[44:45], v45 src0_sel:WORD_1
	global_load_dwordx4 v[118:121], v18, s[10:11]
	global_load_dwordx4 v[114:117], v19, s[10:11]
	v_pk_fma_f32 v[42:43], v[38:39], v[106:107], v[42:43]
	v_cvt_pk_f32_fp8_e32 v[38:39], v47
	v_pk_fma_f32 v[42:43], v[40:41], v[108:109], v[42:43]
	v_lshl_add_u64 v[18:19], v[156:157], 0, s[14:15]
	v_pk_fma_f32 v[42:43], v[34:35], v[110:111], v[42:43]
	s_min_i32 s14, s17, 0x3fff
	v_pk_fma_f32 v[42:43], v[44:45], v[112:113], v[42:43]
	v_cvt_pk_f32_fp8_sdwa v[44:45], v46 src0_sel:WORD_1
	v_add_f32_e32 v40, v42, v43
	v_cvt_pk_f32_fp8_e32 v[42:43], v46
	v_cvt_pk_f32_fp8_sdwa v[46:47], v47 src0_sel:WORD_1
	s_ashr_i32 s15, s14, 31
	s_lshl_b64 s[28:29], s[14:15], 10
	v_pk_fma_f32 v[42:43], v[42:43], v[98:99], 0 op_sel_hi:[1,1,0]
	v_lshl_add_u64 v[30:31], v[154:155], 0, s[28:29]
	v_pk_fma_f32 v[42:43], v[44:45], v[100:101], v[42:43]
	v_cvt_pk_f32_fp8_sdwa v[44:45], v48 src0_sel:WORD_1
	v_pk_fma_f32 v[42:43], v[38:39], v[102:103], v[42:43]
	v_cvt_pk_f32_fp8_e32 v[38:39], v49
	v_pk_fma_f32 v[46:47], v[46:47], v[104:105], v[42:43]
	v_cvt_pk_f32_fp8_e32 v[42:43], v48
	v_cvt_pk_f32_fp8_sdwa v[48:49], v49 src0_sel:WORD_1
	global_load_dwordx4 v[82:85], v[18:19], off offset:48
	global_load_dwordx4 v[86:89], v[18:19], off offset:32
	global_load_dwordx4 v[90:93], v[18:19], off offset:16
	global_load_dwordx4 v[94:97], v[18:19], off
	global_load_dwordx4 v[50:53], v[30:31], off offset:48
	global_load_dwordx4 v[62:65], v[30:31], off offset:32
	s_nop 0
	global_load_dwordx4 v[18:21], v[30:31], off offset:16
	s_nop 0
	global_load_dwordx4 v[30:33], v[30:31], off
	v_pk_fma_f32 v[46:47], v[42:43], v[106:107], v[46:47]
	v_cvt_pk_f32_fp8_e32 v[42:43], v55
	v_pk_fma_f32 v[46:47], v[44:45], v[108:109], v[46:47]
	s_ashr_i32 s19, s18, 31
	v_pk_fma_f32 v[46:47], v[38:39], v[110:111], v[46:47]
	s_lshl_b64 s[18:19], s[18:19], 11
	v_pk_fma_f32 v[46:47], v[48:49], v[112:113], v[46:47]
	v_cvt_pk_f32_fp8_sdwa v[48:49], v54 src0_sel:WORD_1
	v_add_f32_e32 v44, v46, v47
	v_cvt_pk_f32_fp8_e32 v[46:47], v54
	v_cvt_pk_f32_fp8_sdwa v[54:55], v55 src0_sel:WORD_1
	s_add_i32 s12, s22, s12
	s_cmpk_gt_i32 s12, 0x3fff
	v_pk_fma_f32 v[46:47], v[46:47], v[98:99], 0 op_sel_hi:[1,1,0]
	v_readfirstlane_b32 s12, v0
	v_pk_fma_f32 v[46:47], v[48:49], v[100:101], v[46:47]
	v_cvt_pk_f32_fp8_sdwa v[48:49], v56 src0_sel:WORD_1
	v_pk_fma_f32 v[46:47], v[42:43], v[102:103], v[46:47]
	v_cvt_pk_f32_fp8_e32 v[42:43], v57
	v_pk_fma_f32 v[54:55], v[54:55], v[104:105], v[46:47]
	v_cvt_pk_f32_fp8_e32 v[46:47], v56
	v_cvt_pk_f32_fp8_sdwa v[56:57], v57 src0_sel:WORD_1
	v_pk_fma_f32 v[54:55], v[46:47], v[106:107], v[54:55]
	s_nop 0
	v_pk_fma_f32 v[54:55], v[48:49], v[108:109], v[54:55]
	v_cvt_pk_f32_fp8_e32 v[46:47], v59
	v_pk_fma_f32 v[54:55], v[42:43], v[110:111], v[54:55]
; __device__ __forceinline__ f32x2 fp8x2_lo(unsigned w) { return __builtin_amdgcn_cvt_pk_f32_fp8(w, false); }
; __device__ __forceinline__ f32x2 fp8x2_hi(unsigned w) { return __builtin_amdgcn_cvt_pk_f32_fp8(w, true); }
; template <bool NT>
; __device__ __forceinline__ void peer_passA(const Args& a, const PeerWork w) {
;     ...
; #pragma unroll
;         for (int k = 0; k < 16; ++k) {
;             const unsigned ww[4] = {ur[k].x, ur[k].y, ur[k].z, ur[k].w};
;             f32x2 p2 = {0.f, 0.f};
; #pragma unroll
;             for (int wd = 0; wd < 4; ++wd) { p2 = __builtin_elementwise_fma(fp8x2_lo(ww[wd]), (f32x2){hv[wd][0], hv[wd][1]}, p2); p2 = __builtin_elementwise_fma(fp8x2_hi(ww[wd]), (f32x2){hv[wd][2], hv[wd][3]}, p2); }
;             part[k] = p2[0] + p2[1];
	s_nop 0
	v_pk_fma_f32 v[54:55], v[56:57], v[112:113], v[54:55]
	v_cvt_pk_f32_fp8_sdwa v[56:57], v58 src0_sel:WORD_1
	v_add_f32_e32 v48, v54, v55
	v_cvt_pk_f32_fp8_e32 v[54:55], v58
	v_cvt_pk_f32_fp8_sdwa v[58:59], v59 src0_sel:WORD_1
	v_pk_fma_f32 v[54:55], v[54:55], v[98:99], 0 op_sel_hi:[1,1,0]
	s_nop 0
	v_pk_fma_f32 v[54:55], v[56:57], v[100:101], v[54:55]
	v_cvt_pk_f32_fp8_sdwa v[56:57], v60 src0_sel:WORD_1
	v_pk_fma_f32 v[54:55], v[46:47], v[102:103], v[54:55]
	v_cvt_pk_f32_fp8_e32 v[46:47], v61
	v_pk_fma_f32 v[58:59], v[58:59], v[104:105], v[54:55]
	v_cvt_pk_f32_fp8_e32 v[54:55], v60
	v_cvt_pk_f32_fp8_sdwa v[60:61], v61 src0_sel:WORD_1
	v_pk_fma_f32 v[58:59], v[54:55], v[106:107], v[58:59]
	s_nop 0
	v_pk_fma_f32 v[58:59], v[56:57], v[108:109], v[58:59]
	v_cvt_pk_f32_fp8_e32 v[54:55], v67
	v_pk_fma_f32 v[58:59], v[46:47], v[110:111], v[58:59]
	s_nop 0
	v_pk_fma_f32 v[58:59], v[60:61], v[112:113], v[58:59]
	v_cvt_pk_f32_fp8_sdwa v[60:61], v66 src0_sel:WORD_1
	v_add_f32_e32 v56, v58, v59
	v_cvt_pk_f32_fp8_e32 v[58:59], v66
	v_cvt_pk_f32_fp8_sdwa v[66:67], v67 src0_sel:WORD_1
	v_pk_fma_f32 v[58:59], v[58:59], v[98:99], 0 op_sel_hi:[1,1,0]
	s_nop 0
	v_pk_fma_f32 v[58:59], v[60:61], v[100:101], v[58:59]
	v_cvt_pk_f32_fp8_sdwa v[60:61], v68 src0_sel:WORD_1
	v_pk_fma_f32 v[58:59], v[54:55], v[102:103], v[58:59]
	v_cvt_pk_f32_fp8_e32 v[54:55], v69
	v_pk_fma_f32 v[66:67], v[66:67], v[104:105], v[58:59]
	v_cvt_pk_f32_fp8_e32 v[58:59], v68
	v_cvt_pk_f32_fp8_sdwa v[68:69], v69 src0_sel:WORD_1
	v_pk_fma_f32 v[66:67], v[58:59], v[106:107], v[66:67]
	s_nop 0
	v_pk_fma_f32 v[66:67], v[60:61], v[108:109], v[66:67]
	v_cvt_pk_f32_fp8_e32 v[58:59], v71
	v_pk_fma_f32 v[66:67], v[54:55], v[110:111], v[66:67]
	s_nop 0
	v_pk_fma_f32 v[66:67], v[68:69], v[112:113], v[66:67]
	v_cvt_pk_f32_fp8_sdwa v[68:69], v70 src0_sel:WORD_1
	v_add_f32_e32 v60, v66, v67
	v_cvt_pk_f32_fp8_e32 v[66:67], v70
	v_cvt_pk_f32_fp8_sdwa v[70:71], v71 src0_sel:WORD_1
	v_pk_fma_f32 v[66:67], v[66:67], v[98:99], 0 op_sel_hi:[1,1,0]
	s_nop 0
	v_pk_fma_f32 v[66:67], v[68:69], v[100:101], v[66:67]
	v_cvt_pk_f32_fp8_sdwa v[68:69], v72 src0_sel:WORD_1
	v_pk_fma_f32 v[66:67], v[58:59], v[102:103], v[66:67]
	v_cvt_pk_f32_fp8_e32 v[58:59], v73
	v_pk_fma_f32 v[70:71], v[70:71], v[104:105], v[66:67]
	v_cvt_pk_f32_fp8_e32 v[66:67], v72
	v_cvt_pk_f32_fp8_sdwa v[72:73], v73 src0_sel:WORD_1
	v_pk_fma_f32 v[70:71], v[66:67], v[106:107], v[70:71]
	s_nop 0
	v_pk_fma_f32 v[70:71], v[68:69], v[108:109], v[70:71]
	v_cvt_pk_f32_fp8_e32 v[66:67], v75
	v_pk_fma_f32 v[70:71], v[58:59], v[110:111], v[70:71]
	s_nop 0
	v_pk_fma_f32 v[70:71], v[72:73], v[112:113], v[70:71]
	v_cvt_pk_f32_fp8_sdwa v[72:73], v74 src0_sel:WORD_1
	v_add_f32_e32 v68, v70, v71
	v_cvt_pk_f32_fp8_e32 v[70:71], v74
	v_cvt_pk_f32_fp8_sdwa v[74:75], v75 src0_sel:WORD_1
	v_pk_fma_f32 v[70:71], v[70:71], v[98:99], 0 op_sel_hi:[1,1,0]
	s_nop 0
	v_pk_fma_f32 v[70:71], v[72:73], v[100:101], v[70:71]
	v_cvt_pk_f32_fp8_sdwa v[72:73], v76 src0_sel:WORD_1
	v_pk_fma_f32 v[70:71], v[66:67], v[102:103], v[70:71]
	v_cvt_pk_f32_fp8_e32 v[66:67], v77
	v_pk_fma_f32 v[74:75], v[74:75], v[104:105], v[70:71]
	v_cvt_pk_f32_fp8_e32 v[70:71], v76
	v_cvt_pk_f32_fp8_sdwa v[76:77], v77 src0_sel:WORD_1
	v_pk_fma_f32 v[74:75], v[70:71], v[106:107], v[74:75]
	s_nop 0
	v_pk_fma_f32 v[74:75], v[72:73], v[108:109], v[74:75]
	v_cvt_pk_f32_fp8_e32 v[70:71], v79
	v_pk_fma_f32 v[74:75], v[66:67], v[110:111], v[74:75]
	s_nop 0
	v_pk_fma_f32 v[74:75], v[76:77], v[112:113], v[74:75]
	v_cvt_pk_f32_fp8_sdwa v[76:77], v78 src0_sel:WORD_1
	v_add_f32_e32 v72, v74, v75
	v_cvt_pk_f32_fp8_e32 v[74:75], v78
; __device__ __forceinline__ unsigned cvt_pk_bf16(float lo, float hi) { unsigned r; asm volatile("v_cvt_pk_bf16_f32 %0, %1, %2" : "=v"(r) : "v"(lo), "v"(hi)); return r; }
; template <int CTRL> __device__ __forceinline__ float dpp_f(float x) { return __uint_as_float((unsigned)__builtin_amdgcn_update_dpp(0, (int)__float_as_uint(x), CTRL, 0xf, 0xf, false)); }
; __device__ __forceinline__ float xor4_f(float x) { float r = dpp_bank_f<0x104, 0x5>(0.f, x); return dpp_bank_f<0x114, 0xa>(r, x); }
; template <bool NT>
; __device__ __forceinline__ void peer_passA(const Args& a, const PeerWork w) {
;     ...
;             part[k] = p2[0] + p2[1];
;         }
;         float w8[8], w4[4], w2[2];
;         { const bool up = (lane & 4) != 0;
; #pragma unroll
;           for (int m = 0; m < 8; ++m) { const float keep = up ? part[m + 8] : part[m], send = up ? part[m] : part[m + 8]; w8[m] = keep + xor4_f(send); } }
;         { const bool up = (lane & 2) != 0;
; #pragma unroll
;           for (int m = 0; m < 4; ++m) { const float keep = up ? w8[m + 4] : w8[m], send = up ? w8[m] : w8[m + 4]; w4[m] = keep + dpp_f<0x4E>(send); } }
;         { const bool up = (lane & 1) != 0;
; #pragma unroll
;           for (int m = 0; m < 2; ++m) { const float keep = up ? w4[m + 2] : w4[m], send = up ? w4[m] : w4[m + 2]; w2[m] = keep + dpp_f<0xB1>(send); } }
;         PD[(size_t)t * 512] = cvt_pk_bf16(w2[0], w2[1]);
;         if (q + qs > ql) break;
; #pragma unroll
;         for (int k = 0; k < 16; ++k) ur[k] = urn[k];
; #pragma unroll
;         for (int qq = 0; qq < 4; ++qq) hv[qq] = hn[qq];
;         t = t1; t1 = t2;
;     }
	v_cvt_pk_f32_fp8_sdwa v[78:79], v79 src0_sel:WORD_1
	v_pk_fma_f32 v[98:99], v[74:75], v[98:99], 0 op_sel_hi:[1,1,0]
	s_nop 0
	v_pk_fma_f32 v[98:99], v[76:77], v[100:101], v[98:99]
	v_cvt_pk_f32_fp8_e32 v[100:101], v81
	v_pk_fma_f32 v[102:103], v[70:71], v[102:103], v[98:99]
	v_cvt_pk_f32_fp8_sdwa v[98:99], v80 src0_sel:WORD_1
	v_pk_fma_f32 v[102:103], v[78:79], v[104:105], v[102:103]
	v_cvt_pk_f32_fp8_e32 v[104:105], v80
	v_cvt_pk_f32_fp8_sdwa v[78:79], v81 src0_sel:WORD_1
	v_pk_fma_f32 v[106:107], v[104:105], v[106:107], v[102:103]
	s_nop 0
	v_pk_fma_f32 v[106:107], v[98:99], v[108:109], v[106:107]
	v_pk_fma_f32 v[110:111], v[100:101], v[110:111], v[106:107]
	v_pk_fma_f32 v[110:111], v[78:79], v[112:113], v[110:111]
	v_cndmask_b32_e64 v112, v186, v40, s[0:1]
	v_add_f32_e32 v110, v110, v111
	v_cndmask_b32_e64 v111, v40, v186, s[0:1]
	s_nop 0
	v_add_f32_dpp v111, v112, v111 row_half_mirror row_mask:0xf bank_mask:0xf bound_ctrl:1
	v_cndmask_b32_e64 v113, v4, v44, s[0:1]
	v_cndmask_b32_e64 v112, v44, v4, s[0:1]
	s_nop 0
	v_add_f32_dpp v112, v113, v112 row_half_mirror row_mask:0xf bank_mask:0xf bound_ctrl:1
	v_cndmask_b32_e64 v106, v8, v48, s[0:1]
	v_cndmask_b32_e64 v113, v48, v8, s[0:1]
	s_nop 0
	s_nop 0
	v_add_f32_dpp v113, v106, v113 row_half_mirror row_mask:0xf bank_mask:0xf bound_ctrl:1
	v_cndmask_b32_e64 v107, v12, v56, s[0:1]
	v_cndmask_b32_e64 v106, v56, v12, s[0:1]
	s_nop 0
	s_nop 0
	v_add_f32_dpp v106, v107, v106 row_half_mirror row_mask:0xf bank_mask:0xf bound_ctrl:1
	v_cndmask_b32_e64 v108, v16, v60, s[0:1]
	v_cndmask_b32_e64 v107, v60, v16, s[0:1]
	s_nop 0
	s_nop 0
	v_add_f32_dpp v107, v108, v107 row_half_mirror row_mask:0xf bank_mask:0xf bound_ctrl:1
	v_cndmask_b32_e64 v109, v24, v68, s[0:1]
	v_cndmask_b32_e64 v108, v68, v24, s[0:1]
	s_nop 0
	s_nop 0
	v_add_f32_dpp v108, v109, v108 row_half_mirror row_mask:0xf bank_mask:0xf bound_ctrl:1
	v_cndmask_b32_e64 v102, v28, v72, s[0:1]
	v_cndmask_b32_e64 v109, v72, v28, s[0:1]
	s_nop 0
	s_nop 0
	v_add_f32_dpp v109, v102, v109 row_half_mirror row_mask:0xf bank_mask:0xf bound_ctrl:1
	v_cndmask_b32_e64 v102, v110, v36, s[0:1]
	v_cndmask_b32_e64 v110, v36, v110, s[0:1]
	v_mov_b32_e32 v103, 0
	s_nop 1
	s_nop 0
	v_add_f32_dpp v110, v110, v102 row_half_mirror row_mask:0xf bank_mask:0xf bound_ctrl:1
	v_cndmask_b32_e64 v102, v107, v111, s[4:5]
	v_cndmask_b32_e64 v111, v111, v107, s[4:5]
	v_cndmask_b32_e64 v107, v108, v112, s[4:5]
	v_cndmask_b32_e64 v112, v112, v108, s[4:5]
	v_add_f32_dpp v111, v111, v102 quad_perm:[2,3,0,1] row_mask:0xf bank_mask:0xf bound_ctrl:1
	s_nop 0
	v_add_f32_dpp v112, v112, v107 quad_perm:[2,3,0,1] row_mask:0xf bank_mask:0xf bound_ctrl:1
	v_cndmask_b32_e64 v107, v109, v113, s[4:5]
	v_cndmask_b32_e64 v113, v113, v109, s[4:5]
	s_nop 1
	v_add_f32_dpp v113, v113, v107 quad_perm:[2,3,0,1] row_mask:0xf bank_mask:0xf bound_ctrl:1
	v_cndmask_b32_e64 v107, v110, v106, s[4:5]
	v_cndmask_b32_e64 v110, v106, v110, s[4:5]
	v_cndmask_b32_e64 v106, v113, v111, s[6:7]
	v_cndmask_b32_e64 v111, v111, v113, s[6:7]
	v_add_f32_dpp v110, v110, v107 quad_perm:[2,3,0,1] row_mask:0xf bank_mask:0xf bound_ctrl:1
	v_cndmask_b32_e64 v113, v110, v112, s[6:7]
	v_cndmask_b32_e64 v110, v112, v110, s[6:7]
	v_add_f32_dpp v111, v111, v106 quad_perm:[1,0,3,2] row_mask:0xf bank_mask:0xf bound_ctrl:1
	s_nop 0
	v_add_f32_dpp v110, v110, v113 quad_perm:[1,0,3,2] row_mask:0xf bank_mask:0xf bound_ctrl:1
	v_cvt_pk_bf16_f32 v112, v111, v110
	v_lshl_add_u64 v[110:111], v[158:159], 0, s[18:19]
	s_mov_b64 s[18:19], -1
	global_store_dword v[110:111], v112, off
	s_cbranch_scc1 .Lpa_x2_a6
	s_sub_i32 s12, s17, s22
	s_mov_b64 s[18:19], 0
	s_branch .LBB0_1321

; #define PB_IDS(T) do { const unsigned* kp_ = KP + (size_t)(T) * 256; _Pragma("unroll") for (int qq = 0; qq < 4; ++qq) idv[qq] = *(const u32x4*)(kp_ + 4 * qq); } while (0)
; template <bool NT>
; __device__ __forceinline__ void peer_passB(const Args& a, const PeerWork w) {
;     const int lane = threadIdx.x & 63;
;     const int j = w.j, r = lane >> 3, sub = lane & 7;
;     unsigned char* ws = a.ws;
;     const unsigned char* Vs = ws + WS_V8 + (size_t)j * SLICE_BYTES; const unsigned sub16 = 16u * (unsigned)sub;
;     const unsigned* KP = (const unsigned*)(ws + WS_PEERK) + 16 * r;
;     const float* CO = (const float*)(ws + WS_COEF) + 16 * r;
;     const float* H = (const float*)(ws + WS_H) + 128 * j + 16 * sub + 2 * r;
;     float* Y = a.out + 128 * j + 16 * sub + 2 * r;
;     const int qs = w.qstep, ql = w.nq - 1;
;     int q = w.q0;
;     if (q > ql) return;
;     u32x4 idv[4], vr[16]; f32x4 cf[4]; f32x2 hv;
;     ...
;     int t = peer_tok(w, q), t1 = peer_tok(w, min(q + qs, ql));
;     PB_IDS(t);
;     PB_GATHER(t, vr, cf, hv);
;     PB_IDS(t1);
; #pragma unroll 1
;     for (;; q += qs) {
;         u32x4 vrn[16]; f32x4 cfn[4]; f32x2 hn;
;         PB_GATHER(t1, vrn, cfn, hn);
; __global__ void __launch_bounds__(NTHREADS, 2) fwd_kernel(Args args) {
;     ...
;     if (IN(8)) { peer_passB<false>(args, peer_work_plain(wv, NWAVES, NI, 0, NTP)); peer_passA<false>(args, peer_work_plain(wv, NWAVES, NI, NTP, MT)); }
.LBB0_1584:
	s_cmp_lt_i32 s26, 9
	s_cselect_b64 s[8:9], -1, 0
	s_and_b64 s[0:1], s[8:9], s[0:1]
	s_andn2_b64 vcc, exec, s[0:1]
	s_mul_i32 s2, s43, s42
	s_cbranch_vccnz .LBB0_1593
	s_and_b32 s16, s86, 7
	s_ashr_i32 s0, s86, 3
	s_add_i32 s10, s2, s0
	s_and_b32 s22, s3, -8
	s_lshl_b32 s17, s16, 21
	s_add_u32 s0, s24, 0x1b346000
	v_lshlrev_b32_e32 v1, 4, v0
	s_addc_u32 s1, s25, 0
	s_lshl_b32 s4, s16, 9
	v_and_b32_e32 v1, 0x70, v1
	s_add_u32 s4, s24, s4
	s_addc_u32 s5, s25, 0
	s_waitcnt vmcnt(0)
	v_mov_b32_e32 v71, 0
	v_lshlrev_b32_e32 v70, 2, v1
	v_lshl_add_u64 v[2:3], s[4:5], 0, v[70:71]
	s_mov_b64 s[4:5], 0xbb46000
	s_cmpk_gt_i32 s10, 0x3fff
	v_lshl_add_u64 v[178:179], v[2:3], 0, s[4:5]
	s_cbranch_scc1 .LBB0_1588
	s_lshl_b32 s6, s16, 7
	s_add_u32 s4, s24, s17
	s_addc_u32 s5, s25, 0
	s_add_u32 s4, s4, 0x3ca6000
	s_addc_u32 s5, s5, 0
	s_lshl_b32 s6, s6, 2
	v_bfe_u32 v6, v0, 3, 3
	s_add_u32 s12, s94, s6
	v_lshlrev_b32_e32 v2, 6, v6
	v_mov_b32_e32 v3, v71
	s_addc_u32 s13, s95, 0
	s_ashr_i32 s11, s10, 31
	v_lshl_add_u64 v[180:181], s[0:1], 0, v[2:3]
	s_lshl_b64 s[6:7], s[10:11], 10
	v_lshl_add_u64 v[4:5], v[180:181], 0, s[6:7]
	global_load_dwordx4 v[14:17], v[4:5], off
	global_load_dwordx4 v[18:21], v[4:5], off offset:16
	global_load_dwordx4 v[26:29], v[4:5], off offset:32
	global_load_dwordx4 v[30:33], v[4:5], off offset:48
	s_mov_b64 s[6:7], 0x20846000
	v_lshl_add_u64 v[2:3], s[24:25], 0, v[2:3]
	v_lshl_add_u64 v[184:185], v[2:3], 0, s[6:7]
	s_add_i32 s6, s10, s22
	s_min_i32 s6, s6, 0x3fff
	s_lshl_b64 s[14:15], s[10:11], 9
	s_ashr_i32 s7, s6, 31
	v_mov_b32_e32 v73, v71
	v_lshlrev_b32_e32 v72, 3, v6
	v_lshl_add_u64 v[2:3], v[184:185], 0, s[14:15]
	s_lshl_b64 s[14:15], s[6:7], 10
	v_lshl_add_u64 v[182:183], v[178:179], 0, v[72:73]
	s_lshl_b64 s[18:19], s[10:11], 12
	v_lshl_add_u64 v[76:77], v[180:181], 0, s[14:15]
	v_lshl_add_u64 v[74:75], v[182:183], 0, s[18:19]
	global_load_dwordx4 v[22:25], v[2:3], off offset:48
	global_load_dwordx4 v[38:41], v[2:3], off offset:32
	global_load_dwordx4 v[62:65], v[2:3], off offset:16
	global_load_dwordx4 v[162:165], v[2:3], off
	s_nop 0
	global_load_dwordx4 v[2:5], v[76:77], off offset:48
	global_load_dwordx4 v[6:9], v[76:77], off offset:32
	global_load_dwordx4 v[10:13], v[76:77], off offset:16
	v_lshl_add_u64 v[70:71], s[12:13], 0, v[70:71]
	v_lshl_add_u64 v[186:187], v[70:71], 0, v[72:73]
	v_and_b32_e32 v70, 8, v0
	s_lshl_b32 s11, s22, 1
	v_cmp_eq_u32_e32 vcc, 0, v70
	s_mov_b32 s12, s10
	s_mov_b32 s18, s10
	s_waitcnt vmcnt(10)
	v_lshl_or_b32 v14, v14, 7, v1
	v_lshl_or_b32 v15, v15, 7, v1
	v_lshl_or_b32 v16, v16, 7, v1
	v_lshl_or_b32 v17, v17, 7, v1
	s_waitcnt vmcnt(9)
	v_lshl_or_b32 v18, v18, 7, v1
	v_lshl_or_b32 v19, v19, 7, v1
	v_lshl_or_b32 v20, v20, 7, v1
	v_lshl_or_b32 v21, v21, 7, v1
	s_waitcnt vmcnt(8)
	v_lshl_or_b32 v78, v26, 7, v1
	v_lshl_or_b32 v79, v27, 7, v1
	v_lshl_or_b32 v80, v28, 7, v1
	v_lshl_or_b32 v81, v29, 7, v1
	s_waitcnt vmcnt(7)
	v_lshl_or_b32 v82, v30, 7, v1
	v_lshl_or_b32 v83, v31, 7, v1
	v_lshl_or_b32 v84, v32, 7, v1
	v_lshl_or_b32 v85, v33, 7, v1
	global_load_dwordx4 v[174:177], v14, s[4:5]
	global_load_dwordx4 v[170:173], v15, s[4:5]
	global_load_dwordx4 v[166:169], v16, s[4:5]
	global_load_dwordx4 v[158:161], v17, s[4:5]
	global_load_dwordx4 v[138:141], v18, s[4:5]
	global_load_dwordx4 v[94:97], v19, s[4:5]
	global_load_dwordx4 v[66:69], v20, s[4:5]
	global_load_dwordx4 v[58:61], v21, s[4:5]
	global_load_dwordx4 v[54:57], v78, s[4:5]
	global_load_dwordx4 v[50:53], v79, s[4:5]
	global_load_dwordx4 v[46:49], v80, s[4:5]
	global_load_dwordx4 v[42:45], v81, s[4:5]
	global_load_dwordx4 v[34:37], v82, s[4:5]
	global_load_dwordx4 v[30:33], v83, s[4:5]
	global_load_dwordx4 v[26:29], v84, s[4:5]
	global_load_dwordx4 v[18:21], v85, s[4:5]
	global_load_dwordx2 v[190:191], v[74:75], off
	global_load_dwordx4 v[14:17], v[76:77], off
	s_waitcnt vmcnt(0)
	s_cmp_lt_u32 s42, 4
	s_cbranch_scc1 .Lstag_b
	s_sleep 39
.Lstag_b:
.LBB0_1587:
	s_waitcnt vmcnt(23)
	v_cvt_pk_f32_fp8_e32 v[192:193], v174
	s_waitcnt vmcnt(19)
	v_cvt_pk_f32_fp8_e32 v[204:205], v170
	v_cvt_pk_f32_fp8_sdwa v[194:195], v174 src0_sel:WORD_1
	v_cvt_pk_f32_fp8_e32 v[196:197], v175
	s_waitcnt vmcnt(6)
	v_pk_fma_f32 v[192:193], v[192:193], v[162:163], 0 op_sel_hi:[1,0,0]
	v_cvt_pk_f32_fp8_sdwa v[174:175], v175 src0_sel:WORD_1
	v_pk_fma_f32 v[192:193], v[204:205], v[162:163], v[192:193] op_sel:[0,1,0]
	v_cvt_pk_f32_fp8_sdwa v[204:205], v170 src0_sel:WORD_1
	v_pk_fma_f32 v[194:195], v[194:195], v[162:163], 0 op_sel_hi:[1,0,0]
	v_pk_fma_f32 v[174:175], v[174:175], v[162:163], 0 op_sel_hi:[1,0,0]
	v_cvt_pk_f32_fp8_e32 v[198:199], v176
	v_pk_fma_f32 v[194:195], v[204:205], v[162:163], v[194:195] op_sel:[0,1,0]
	v_cvt_pk_f32_fp8_e32 v[204:205], v171
	v_cvt_pk_f32_fp8_sdwa v[170:171], v171 src0_sel:WORD_1
	v_pk_fma_f32 v[198:199], v[198:199], v[162:163], 0 op_sel_hi:[1,0,0]
	v_cvt_pk_f32_fp8_sdwa v[200:201], v176 src0_sel:WORD_1
	v_cvt_pk_f32_fp8_e32 v[202:203], v177
	v_pk_fma_f32 v[170:171], v[170:171], v[162:163], v[174:175] op_sel:[0,1,0]
	v_cvt_pk_f32_fp8_e32 v[174:175], v172
	v_pk_fma_f32 v[200:201], v[200:201], v[162:163], 0 op_sel_hi:[1,0,0]
	v_cvt_pk_f32_fp8_sdwa v[176:177], v177 src0_sel:WORD_1
	v_pk_fma_f32 v[196:197], v[196:197], v[162:163], 0 op_sel_hi:[1,0,0]
	v_pk_fma_f32 v[174:175], v[174:175], v[162:163], v[198:199] op_sel:[0,1,0]
	v_cvt_pk_f32_fp8_sdwa v[198:199], v172 src0_sel:WORD_1
	v_pk_fma_f32 v[202:203], v[202:203], v[162:163], 0 op_sel_hi:[1,0,0]
	v_pk_fma_f32 v[176:177], v[176:177], v[162:163], 0 op_sel_hi:[1,0,0]
	v_pk_fma_f32 v[196:197], v[204:205], v[162:163], v[196:197] op_sel:[0,1,0]
	v_pk_fma_f32 v[198:199], v[198:199], v[162:163], v[200:201] op_sel:[0,1,0]
	v_cvt_pk_f32_fp8_e32 v[200:201], v173
	v_cvt_pk_f32_fp8_sdwa v[172:173], v173 src0_sel:WORD_1
	s_waitcnt vmcnt(3)
; __device__ __forceinline__ f32x2 fp8x2_lo(unsigned w) { return __builtin_amdgcn_cvt_pk_f32_fp8(w, false); }
; __device__ __forceinline__ f32x2 fp8x2_hi(unsigned w) { return __builtin_amdgcn_cvt_pk_f32_fp8(w, true); }
; #define PB_IDS(T) do { const unsigned* kp_ = KP + (size_t)(T) * 256; _Pragma("unroll") for (int qq = 0; qq < 4; ++qq) idv[qq] = *(const u32x4*)(kp_ + 4 * qq); } while (0)
; template <bool NT>
; __device__ __forceinline__ void peer_passB(const Args& a, const PeerWork w) {
;     ...
;     int t = peer_tok(w, q), t1 = peer_tok(w, min(q + qs, ql));
;     PB_IDS(t);
;     PB_GATHER(t, vr, cf, hv);
;     PB_IDS(t1);
; #pragma unroll 1
;     for (;; q += qs) {
;         u32x4 vrn[16]; f32x4 cfn[4]; f32x2 hn;
;         PB_GATHER(t1, vrn, cfn, hn);
;         const int t2 = peer_tok(w, min(q + 2 * qs, ql));
;         PB_IDS(t2);
;         f32x2 acc[8];
; #pragma unroll
;         for (int m = 0; m < 8; ++m) acc[m] = (f32x2){0.f, 0.f};
; #pragma unroll
;         for (int k = 0; k < 16; ++k) {
;             const unsigned ww[4] = {vr[k].x, vr[k].y, vr[k].z, vr[k].w};
;             const float c = cf[k >> 2][k & 3]; const f32x2 c2 = {c, c};
; #pragma unroll
;             for (int wd = 0; wd < 4; ++wd) { acc[2 * wd] = __builtin_elementwise_fma(fp8x2_lo(ww[wd]), c2, acc[2 * wd]); acc[2 * wd + 1] = __builtin_elementwise_fma(fp8x2_hi(ww[wd]), c2, acc[2 * wd + 1]); }
	v_lshl_or_b32 v6, v6, 7, v1
	v_lshl_or_b32 v2, v2, 7, v1
	v_pk_fma_f32 v[200:201], v[200:201], v[162:163], v[202:203] op_sel:[0,1,0]
	v_pk_fma_f32 v[162:163], v[172:173], v[162:163], v[176:177] op_sel:[0,1,0]
	v_cvt_pk_f32_fp8_e32 v[172:173], v166
	v_cvt_pk_f32_fp8_sdwa v[176:177], v166 src0_sel:WORD_1
	s_waitcnt vmcnt(1)
	v_lshl_or_b32 v14, v14, 7, v1
	v_lshl_or_b32 v10, v10, 7, v1
	v_pk_fma_f32 v[172:173], v[172:173], v[164:165], v[192:193] op_sel_hi:[1,0,1]
	v_cvt_pk_f32_fp8_e32 v[192:193], v167
	v_cvt_pk_f32_fp8_sdwa v[166:167], v167 src0_sel:WORD_1
	v_pk_fma_f32 v[176:177], v[176:177], v[164:165], v[194:195] op_sel_hi:[1,0,1]
	v_cvt_pk_f32_fp8_e32 v[194:195], v169
	v_pk_fma_f32 v[192:193], v[192:193], v[164:165], v[196:197] op_sel_hi:[1,0,1]
	v_pk_fma_f32 v[166:167], v[166:167], v[164:165], v[170:171] op_sel_hi:[1,0,1]
	v_cvt_pk_f32_fp8_e32 v[170:171], v168
	v_pk_fma_f32 v[194:195], v[194:195], v[164:165], v[200:201] op_sel_hi:[1,0,1]
	global_load_dwordx4 v[106:109], v6, s[4:5]
	global_load_dwordx4 v[122:125], v2, s[4:5]
	v_pk_fma_f32 v[170:171], v[170:171], v[164:165], v[174:175] op_sel_hi:[1,0,1]
	v_cvt_pk_f32_fp8_sdwa v[174:175], v168 src0_sel:WORD_1
	v_cvt_pk_f32_fp8_sdwa v[168:169], v169 src0_sel:WORD_1
	v_lshl_or_b32 v6, v7, 7, v1
	v_lshl_or_b32 v2, v3, 7, v1
	v_pk_fma_f32 v[174:175], v[174:175], v[164:165], v[198:199] op_sel_hi:[1,0,1]
	v_pk_fma_f32 v[162:163], v[168:169], v[164:165], v[162:163] op_sel_hi:[1,0,1]
	v_cvt_pk_f32_fp8_e32 v[168:169], v158
	v_mov_b32_e32 v164, v165
	s_mov_b32 s14, s6
	global_load_dwordx4 v[70:73], v14, s[4:5]
	global_load_dwordx4 v[86:89], v10, s[4:5]
	v_pk_fma_f32 v[168:169], v[168:169], v[164:165], v[172:173] op_sel_hi:[1,0,1]
	v_cvt_pk_f32_fp8_sdwa v[172:173], v158 src0_sel:WORD_1
	v_lshl_or_b32 v14, v15, 7, v1
	v_lshl_or_b32 v10, v11, 7, v1
	global_load_dwordx4 v[110:113], v6, s[4:5]
	global_load_dwordx4 v[126:129], v2, s[4:5]
	v_pk_fma_f32 v[172:173], v[172:173], v[164:165], v[176:177] op_sel_hi:[1,0,1]
	v_cvt_pk_f32_fp8_e32 v[176:177], v159
	v_cvt_pk_f32_fp8_sdwa v[158:159], v159 src0_sel:WORD_1
	v_lshl_or_b32 v6, v8, 7, v1
	v_lshl_or_b32 v2, v4, 7, v1
	v_pk_fma_f32 v[176:177], v[176:177], v[164:165], v[192:193] op_sel_hi:[1,0,1]
	v_pk_fma_f32 v[158:159], v[158:159], v[164:165], v[166:167] op_sel_hi:[1,0,1]
	v_cvt_pk_f32_fp8_e32 v[166:167], v160
	s_ashr_i32 s15, s6, 31
	global_load_dwordx4 v[74:77], v14, s[4:5]
	global_load_dwordx4 v[90:93], v10, s[4:5]
	v_pk_fma_f32 v[166:167], v[166:167], v[164:165], v[170:171] op_sel_hi:[1,0,1]
	v_cvt_pk_f32_fp8_sdwa v[170:171], v160 src0_sel:WORD_1
	v_lshl_or_b32 v14, v16, 7, v1
	v_lshl_or_b32 v10, v12, 7, v1
	global_load_dwordx4 v[114:117], v6, s[4:5]
	global_load_dwordx4 v[130:133], v2, s[4:5]
	v_pk_fma_f32 v[170:171], v[170:171], v[164:165], v[174:175] op_sel_hi:[1,0,1]
	v_cvt_pk_f32_fp8_e32 v[174:175], v161
	v_cvt_pk_f32_fp8_sdwa v[160:161], v161 src0_sel:WORD_1
	v_lshl_or_b32 v6, v9, 7, v1
	v_lshl_or_b32 v2, v5, 7, v1
	v_pk_fma_f32 v[174:175], v[174:175], v[164:165], v[194:195] op_sel_hi:[1,0,1]
	v_pk_fma_f32 v[160:161], v[160:161], v[164:165], v[162:163] op_sel_hi:[1,0,1]
	v_cvt_pk_f32_fp8_e32 v[162:163], v138
	v_cvt_pk_f32_fp8_sdwa v[164:165], v138 src0_sel:WORD_1
	s_lshl_b64 s[6:7], s[14:15], 9
	global_load_dwordx4 v[78:81], v14, s[4:5]
	global_load_dwordx4 v[98:101], v10, s[4:5]
	v_pk_fma_f32 v[162:163], v[162:163], v[62:63], v[168:169] op_sel_hi:[1,0,1]
	v_cvt_pk_f32_fp8_e32 v[168:169], v139
	v_cvt_pk_f32_fp8_sdwa v[138:139], v139 src0_sel:WORD_1
	v_pk_fma_f32 v[164:165], v[164:165], v[62:63], v[172:173] op_sel_hi:[1,0,1]
	v_lshl_or_b32 v14, v17, 7, v1
	v_pk_fma_f32 v[168:169], v[168:169], v[62:63], v[176:177] op_sel_hi:[1,0,1]
	v_pk_fma_f32 v[138:139], v[138:139], v[62:63], v[158:159] op_sel_hi:[1,0,1]
	v_cvt_pk_f32_fp8_e32 v[158:159], v140
	v_lshl_or_b32 v10, v13, 7, v1
	global_load_dwordx4 v[118:121], v6, s[4:5]
	global_load_dwordx4 v[134:137], v2, s[4:5]
	v_pk_fma_f32 v[158:159], v[158:159], v[62:63], v[166:167] op_sel_hi:[1,0,1]
	v_cvt_pk_f32_fp8_sdwa v[166:167], v140 src0_sel:WORD_1
	v_lshl_add_u64 v[2:3], v[184:185], 0, s[6:7]
	s_lshl_b64 s[6:7], s[14:15], 12
	global_load_dwordx4 v[82:85], v14, s[4:5]
	global_load_dwordx4 v[102:105], v10, s[4:5]
	v_pk_fma_f32 v[166:167], v[166:167], v[62:63], v[170:171] op_sel_hi:[1,0,1]
	v_cvt_pk_f32_fp8_e32 v[170:171], v141
	v_cvt_pk_f32_fp8_sdwa v[140:141], v141 src0_sel:WORD_1
	global_load_dwordx4 v[142:145], v[2:3], off offset:48
	global_load_dwordx4 v[146:149], v[2:3], off offset:32
	global_load_dwordx4 v[150:153], v[2:3], off offset:16
	global_load_dwordx4 v[154:157], v[2:3], off
	v_lshl_add_u64 v[2:3], v[182:183], 0, s[6:7]
	v_pk_fma_f32 v[170:171], v[170:171], v[62:63], v[174:175] op_sel_hi:[1,0,1]
	v_pk_fma_f32 v[140:141], v[140:141], v[62:63], v[160:161] op_sel_hi:[1,0,1]
	v_cvt_pk_f32_fp8_e32 v[160:161], v94
	s_add_i32 s6, s11, s18
	s_min_i32 s6, s6, 0x3fff
	s_ashr_i32 s7, s6, 31
	v_pk_fma_f32 v[160:161], v[160:161], v[62:63], v[162:163] op_sel:[0,1,0]
	v_cvt_pk_f32_fp8_sdwa v[162:163], v94 src0_sel:WORD_1
	s_lshl_b64 s[28:29], s[6:7], 10
	v_lshl_add_u64 v[14:15], v[180:181], 0, s[28:29]
	global_load_dwordx2 v[188:189], v[2:3], off
	v_pk_fma_f32 v[162:163], v[162:163], v[62:63], v[164:165] op_sel:[0,1,0]
	v_cvt_pk_f32_fp8_e32 v[164:165], v95
	v_cvt_pk_f32_fp8_sdwa v[94:95], v95 src0_sel:WORD_1
	global_load_dwordx4 v[2:5], v[14:15], off offset:48
	global_load_dwordx4 v[6:9], v[14:15], off offset:32
	global_load_dwordx4 v[10:13], v[14:15], off offset:16
	s_nop 0
	global_load_dwordx4 v[14:17], v[14:15], off
	s_ashr_i32 s13, s12, 31
	v_pk_fma_f32 v[164:165], v[164:165], v[62:63], v[168:169] op_sel:[0,1,0]
; __device__ __forceinline__ f32x2 fp8x2_lo(unsigned w) { return __builtin_amdgcn_cvt_pk_f32_fp8(w, false); }
; __device__ __forceinline__ f32x2 fp8x2_hi(unsigned w) { return __builtin_amdgcn_cvt_pk_f32_fp8(w, true); }
; template <bool NT>
; __device__ __forceinline__ void peer_passB(const Args& a, const PeerWork w) {
;     ...
;         for (int k = 0; k < 16; ++k) {
;             const unsigned ww[4] = {vr[k].x, vr[k].y, vr[k].z, vr[k].w};
;             const float c = cf[k >> 2][k & 3]; const f32x2 c2 = {c, c};
; #pragma unroll
;             for (int wd = 0; wd < 4; ++wd) { acc[2 * wd] = __builtin_elementwise_fma(fp8x2_lo(ww[wd]), c2, acc[2 * wd]); acc[2 * wd + 1] = __builtin_elementwise_fma(fp8x2_hi(ww[wd]), c2, acc[2 * wd + 1]); }
;         }
	v_pk_fma_f32 v[94:95], v[94:95], v[62:63], v[138:139] op_sel:[0,1,0]
	v_cvt_pk_f32_fp8_e32 v[138:139], v96
	s_lshl_b64 s[12:13], s[12:13], 12
	s_add_i32 s18, s18, s22
	v_pk_fma_f32 v[138:139], v[138:139], v[62:63], v[158:159] op_sel:[0,1,0]
	v_cvt_pk_f32_fp8_sdwa v[158:159], v96 src0_sel:WORD_1
	s_cmpk_lt_i32 s18, 0x4000
	v_pk_fma_f32 v[158:159], v[158:159], v[62:63], v[166:167] op_sel:[0,1,0]
	v_cvt_pk_f32_fp8_e32 v[166:167], v97
	v_cvt_pk_f32_fp8_sdwa v[96:97], v97 src0_sel:WORD_1
	v_pk_fma_f32 v[166:167], v[166:167], v[62:63], v[170:171] op_sel:[0,1,0]
	v_pk_fma_f32 v[62:63], v[96:97], v[62:63], v[140:141] op_sel:[0,1,0]
	v_cvt_pk_f32_fp8_e32 v[96:97], v66
	v_cvt_pk_f32_fp8_sdwa v[140:141], v66 src0_sel:WORD_1
	v_pk_fma_f32 v[96:97], v[96:97], v[64:65], v[160:161] op_sel_hi:[1,0,1]
	v_cvt_pk_f32_fp8_e32 v[160:161], v67
	v_cvt_pk_f32_fp8_sdwa v[66:67], v67 src0_sel:WORD_1
	v_pk_fma_f32 v[140:141], v[140:141], v[64:65], v[162:163] op_sel_hi:[1,0,1]
	v_pk_fma_f32 v[160:161], v[160:161], v[64:65], v[164:165] op_sel_hi:[1,0,1]
	v_pk_fma_f32 v[66:67], v[66:67], v[64:65], v[94:95] op_sel_hi:[1,0,1]
	v_cvt_pk_f32_fp8_e32 v[94:95], v68
	v_pk_fma_f32 v[94:95], v[94:95], v[64:65], v[138:139] op_sel_hi:[1,0,1]
	v_cvt_pk_f32_fp8_sdwa v[138:139], v68 src0_sel:WORD_1
	v_pk_fma_f32 v[138:139], v[138:139], v[64:65], v[158:159] op_sel_hi:[1,0,1]
	v_cvt_pk_f32_fp8_e32 v[158:159], v69
	v_cvt_pk_f32_fp8_sdwa v[68:69], v69 src0_sel:WORD_1
	v_pk_fma_f32 v[158:159], v[158:159], v[64:65], v[166:167] op_sel_hi:[1,0,1]
	v_pk_fma_f32 v[62:63], v[68:69], v[64:65], v[62:63] op_sel_hi:[1,0,1]
	v_cvt_pk_f32_fp8_e32 v[68:69], v58
	v_mov_b32_e32 v64, v65
	v_pk_fma_f32 v[68:69], v[68:69], v[64:65], v[96:97] op_sel_hi:[1,0,1]
	v_cvt_pk_f32_fp8_sdwa v[96:97], v58 src0_sel:WORD_1
	v_pk_fma_f32 v[96:97], v[96:97], v[64:65], v[140:141] op_sel_hi:[1,0,1]
	v_cvt_pk_f32_fp8_e32 v[140:141], v59
	v_cvt_pk_f32_fp8_sdwa v[58:59], v59 src0_sel:WORD_1
	v_pk_fma_f32 v[140:141], v[140:141], v[64:65], v[160:161] op_sel_hi:[1,0,1]
	v_pk_fma_f32 v[58:59], v[58:59], v[64:65], v[66:67] op_sel_hi:[1,0,1]
	v_cvt_pk_f32_fp8_e32 v[66:67], v60
	v_pk_fma_f32 v[66:67], v[66:67], v[64:65], v[94:95] op_sel_hi:[1,0,1]
	v_cvt_pk_f32_fp8_sdwa v[94:95], v60 src0_sel:WORD_1
	v_pk_fma_f32 v[94:95], v[94:95], v[64:65], v[138:139] op_sel_hi:[1,0,1]
	v_cvt_pk_f32_fp8_e32 v[138:139], v61
	v_cvt_pk_f32_fp8_sdwa v[60:61], v61 src0_sel:WORD_1
	v_pk_fma_f32 v[138:139], v[138:139], v[64:65], v[158:159] op_sel_hi:[1,0,1]
	v_pk_fma_f32 v[60:61], v[60:61], v[64:65], v[62:63] op_sel_hi:[1,0,1]
	v_cvt_pk_f32_fp8_e32 v[62:63], v54
	v_cvt_pk_f32_fp8_sdwa v[64:65], v54 src0_sel:WORD_1
	v_pk_fma_f32 v[62:63], v[62:63], v[38:39], v[68:69] op_sel_hi:[1,0,1]
	v_cvt_pk_f32_fp8_e32 v[68:69], v55
	v_cvt_pk_f32_fp8_sdwa v[54:55], v55 src0_sel:WORD_1
	v_pk_fma_f32 v[64:65], v[64:65], v[38:39], v[96:97] op_sel_hi:[1,0,1]
	v_pk_fma_f32 v[68:69], v[68:69], v[38:39], v[140:141] op_sel_hi:[1,0,1]
	v_pk_fma_f32 v[54:55], v[54:55], v[38:39], v[58:59] op_sel_hi:[1,0,1]
	v_cvt_pk_f32_fp8_e32 v[58:59], v56
	v_pk_fma_f32 v[58:59], v[58:59], v[38:39], v[66:67] op_sel_hi:[1,0,1]
	v_cvt_pk_f32_fp8_sdwa v[66:67], v56 src0_sel:WORD_1
	v_pk_fma_f32 v[66:67], v[66:67], v[38:39], v[94:95] op_sel_hi:[1,0,1]
	v_cvt_pk_f32_fp8_e32 v[94:95], v57
	v_cvt_pk_f32_fp8_sdwa v[56:57], v57 src0_sel:WORD_1
	v_pk_fma_f32 v[94:95], v[94:95], v[38:39], v[138:139] op_sel_hi:[1,0,1]
	v_pk_fma_f32 v[56:57], v[56:57], v[38:39], v[60:61] op_sel_hi:[1,0,1]
	v_cvt_pk_f32_fp8_e32 v[60:61], v50
	v_pk_fma_f32 v[60:61], v[60:61], v[38:39], v[62:63] op_sel:[0,1,0]
	v_cvt_pk_f32_fp8_sdwa v[62:63], v50 src0_sel:WORD_1
	v_pk_fma_f32 v[62:63], v[62:63], v[38:39], v[64:65] op_sel:[0,1,0]
	v_cvt_pk_f32_fp8_e32 v[64:65], v51
	v_cvt_pk_f32_fp8_sdwa v[50:51], v51 src0_sel:WORD_1
	v_pk_fma_f32 v[64:65], v[64:65], v[38:39], v[68:69] op_sel:[0,1,0]
	v_pk_fma_f32 v[50:51], v[50:51], v[38:39], v[54:55] op_sel:[0,1,0]
	v_cvt_pk_f32_fp8_e32 v[54:55], v52
	v_pk_fma_f32 v[54:55], v[54:55], v[38:39], v[58:59] op_sel:[0,1,0]
	v_cvt_pk_f32_fp8_sdwa v[58:59], v52 src0_sel:WORD_1
	v_pk_fma_f32 v[58:59], v[58:59], v[38:39], v[66:67] op_sel:[0,1,0]
	v_cvt_pk_f32_fp8_e32 v[66:67], v53
	v_cvt_pk_f32_fp8_sdwa v[52:53], v53 src0_sel:WORD_1
	v_pk_fma_f32 v[66:67], v[66:67], v[38:39], v[94:95] op_sel:[0,1,0]
	v_pk_fma_f32 v[38:39], v[52:53], v[38:39], v[56:57] op_sel:[0,1,0]
	v_cvt_pk_f32_fp8_e32 v[52:53], v46
	v_cvt_pk_f32_fp8_sdwa v[56:57], v46 src0_sel:WORD_1
	v_pk_fma_f32 v[52:53], v[52:53], v[40:41], v[60:61] op_sel_hi:[1,0,1]
	v_cvt_pk_f32_fp8_e32 v[60:61], v47
	v_cvt_pk_f32_fp8_sdwa v[46:47], v47 src0_sel:WORD_1
	v_pk_fma_f32 v[56:57], v[56:57], v[40:41], v[62:63] op_sel_hi:[1,0,1]
	v_pk_fma_f32 v[60:61], v[60:61], v[40:41], v[64:65] op_sel_hi:[1,0,1]
	v_pk_fma_f32 v[46:47], v[46:47], v[40:41], v[50:51] op_sel_hi:[1,0,1]
	v_cvt_pk_f32_fp8_e32 v[50:51], v48
	v_pk_fma_f32 v[50:51], v[50:51], v[40:41], v[54:55] op_sel_hi:[1,0,1]
	v_cvt_pk_f32_fp8_sdwa v[54:55], v48 src0_sel:WORD_1
	v_pk_fma_f32 v[54:55], v[54:55], v[40:41], v[58:59] op_sel_hi:[1,0,1]
	v_cvt_pk_f32_fp8_e32 v[58:59], v49
	v_cvt_pk_f32_fp8_sdwa v[48:49], v49 src0_sel:WORD_1
	v_pk_fma_f32 v[58:59], v[58:59], v[40:41], v[66:67] op_sel_hi:[1,0,1]
	v_pk_fma_f32 v[38:39], v[48:49], v[40:41], v[38:39] op_sel_hi:[1,0,1]
	v_cvt_pk_f32_fp8_e32 v[48:49], v42
	v_mov_b32_e32 v40, v41
	v_pk_fma_f32 v[48:49], v[48:49], v[40:41], v[52:53] op_sel_hi:[1,0,1]
	v_cvt_pk_f32_fp8_sdwa v[52:53], v42 src0_sel:WORD_1
	v_pk_fma_f32 v[52:53], v[52:53], v[40:41], v[56:57] op_sel_hi:[1,0,1]
	v_cvt_pk_f32_fp8_e32 v[56:57], v43
	v_cvt_pk_f32_fp8_sdwa v[42:43], v43 src0_sel:WORD_1
; template <int CTRL> __device__ __forceinline__ float dpp_f(float x) { return __uint_as_float((unsigned)__builtin_amdgcn_update_dpp(0, (int)__float_as_uint(x), CTRL, 0xf, 0xf, false)); }
; __device__ __forceinline__ f32x2 fp8x2_lo(unsigned w) { return __builtin_amdgcn_cvt_pk_f32_fp8(w, false); }
; __device__ __forceinline__ f32x2 fp8x2_hi(unsigned w) { return __builtin_amdgcn_cvt_pk_f32_fp8(w, true); }
; template <bool NT>
; __device__ __forceinline__ void peer_passB(const Args& a, const PeerWork w) {
;     ...
;         for (int k = 0; k < 16; ++k) {
;             const unsigned ww[4] = {vr[k].x, vr[k].y, vr[k].z, vr[k].w};
;             const float c = cf[k >> 2][k & 3]; const f32x2 c2 = {c, c};
; #pragma unroll
;             for (int wd = 0; wd < 4; ++wd) { acc[2 * wd] = __builtin_elementwise_fma(fp8x2_lo(ww[wd]), c2, acc[2 * wd]); acc[2 * wd + 1] = __builtin_elementwise_fma(fp8x2_hi(ww[wd]), c2, acc[2 * wd + 1]); }
;         }
;         float w8[8], w4[4], w2[2];
; #pragma unroll
;         for (int m = 0; m < 8; ++m) { const auto sw = __builtin_amdgcn_permlane32_swap(__float_as_uint(acc[m >> 1][m & 1]), __float_as_uint(acc[(m + 8) >> 1][m & 1]), false, false); w8[m] = __uint_as_float(sw[0]) + __uint_as_float(sw[1]); }
; #pragma unroll
;         for (int m = 0; m < 4; ++m) { const auto sw = __builtin_amdgcn_permlane16_swap(__float_as_uint(w8[m]), __float_as_uint(w8[m + 4]), false, false); w4[m] = __uint_as_float(sw[0]) + __uint_as_float(sw[1]); }
;         { const bool up = (lane & 8) != 0;
; #pragma unroll
;           for (int m = 0; m < 2; ++m) { const float keep = up ? w4[m + 2] : w4[m], send = up ? w4[m] : w4[m + 2]; w2[m] = keep + dpp_f<0x128>(send); } }
;         *(f32x2*)(Y + (size_t)t * DM) = (f32x2){hv[0] + w2[0], hv[1] + w2[1]};
;         if (q + qs > ql) break;
	v_pk_fma_f32 v[56:57], v[56:57], v[40:41], v[60:61] op_sel_hi:[1,0,1]
	v_pk_fma_f32 v[42:43], v[42:43], v[40:41], v[46:47] op_sel_hi:[1,0,1]
	v_cvt_pk_f32_fp8_e32 v[46:47], v44
	v_pk_fma_f32 v[46:47], v[46:47], v[40:41], v[50:51] op_sel_hi:[1,0,1]
	v_cvt_pk_f32_fp8_sdwa v[50:51], v44 src0_sel:WORD_1
	v_pk_fma_f32 v[50:51], v[50:51], v[40:41], v[54:55] op_sel_hi:[1,0,1]
	v_cvt_pk_f32_fp8_e32 v[54:55], v45
	v_cvt_pk_f32_fp8_sdwa v[44:45], v45 src0_sel:WORD_1
	v_pk_fma_f32 v[54:55], v[54:55], v[40:41], v[58:59] op_sel_hi:[1,0,1]
	v_pk_fma_f32 v[38:39], v[44:45], v[40:41], v[38:39] op_sel_hi:[1,0,1]
	v_cvt_pk_f32_fp8_e32 v[40:41], v34
	v_cvt_pk_f32_fp8_sdwa v[44:45], v34 src0_sel:WORD_1
	v_pk_fma_f32 v[40:41], v[40:41], v[22:23], v[48:49] op_sel_hi:[1,0,1]
	v_cvt_pk_f32_fp8_e32 v[48:49], v35
	v_cvt_pk_f32_fp8_sdwa v[34:35], v35 src0_sel:WORD_1
	v_pk_fma_f32 v[44:45], v[44:45], v[22:23], v[52:53] op_sel_hi:[1,0,1]
	v_pk_fma_f32 v[48:49], v[48:49], v[22:23], v[56:57] op_sel_hi:[1,0,1]
	v_pk_fma_f32 v[34:35], v[34:35], v[22:23], v[42:43] op_sel_hi:[1,0,1]
	v_cvt_pk_f32_fp8_e32 v[42:43], v36
	v_pk_fma_f32 v[42:43], v[42:43], v[22:23], v[46:47] op_sel_hi:[1,0,1]
	v_cvt_pk_f32_fp8_sdwa v[46:47], v36 src0_sel:WORD_1
	v_pk_fma_f32 v[46:47], v[46:47], v[22:23], v[50:51] op_sel_hi:[1,0,1]
	v_cvt_pk_f32_fp8_e32 v[50:51], v37
	v_cvt_pk_f32_fp8_sdwa v[36:37], v37 src0_sel:WORD_1
	v_pk_fma_f32 v[50:51], v[50:51], v[22:23], v[54:55] op_sel_hi:[1,0,1]
	v_pk_fma_f32 v[36:37], v[36:37], v[22:23], v[38:39] op_sel_hi:[1,0,1]
	v_cvt_pk_f32_fp8_e32 v[38:39], v30
	v_pk_fma_f32 v[38:39], v[38:39], v[22:23], v[40:41] op_sel:[0,1,0]
	v_cvt_pk_f32_fp8_sdwa v[40:41], v30 src0_sel:WORD_1
	v_pk_fma_f32 v[40:41], v[40:41], v[22:23], v[44:45] op_sel:[0,1,0]
	v_cvt_pk_f32_fp8_e32 v[44:45], v31
	v_cvt_pk_f32_fp8_sdwa v[30:31], v31 src0_sel:WORD_1
	v_pk_fma_f32 v[44:45], v[44:45], v[22:23], v[48:49] op_sel:[0,1,0]
	v_pk_fma_f32 v[30:31], v[30:31], v[22:23], v[34:35] op_sel:[0,1,0]
	v_cvt_pk_f32_fp8_e32 v[34:35], v32
	v_pk_fma_f32 v[34:35], v[34:35], v[22:23], v[42:43] op_sel:[0,1,0]
	v_cvt_pk_f32_fp8_sdwa v[42:43], v32 src0_sel:WORD_1
	v_pk_fma_f32 v[42:43], v[42:43], v[22:23], v[46:47] op_sel:[0,1,0]
	v_cvt_pk_f32_fp8_e32 v[46:47], v33
	v_cvt_pk_f32_fp8_sdwa v[32:33], v33 src0_sel:WORD_1
	v_pk_fma_f32 v[46:47], v[46:47], v[22:23], v[50:51] op_sel:[0,1,0]
	v_pk_fma_f32 v[22:23], v[32:33], v[22:23], v[36:37] op_sel:[0,1,0]
	v_cvt_pk_f32_fp8_e32 v[32:33], v26
	v_cvt_pk_f32_fp8_sdwa v[36:37], v26 src0_sel:WORD_1
	v_pk_fma_f32 v[32:33], v[32:33], v[24:25], v[38:39] op_sel_hi:[1,0,1]
	v_cvt_pk_f32_fp8_e32 v[38:39], v27
	v_cvt_pk_f32_fp8_sdwa v[26:27], v27 src0_sel:WORD_1
	v_pk_fma_f32 v[36:37], v[36:37], v[24:25], v[40:41] op_sel_hi:[1,0,1]
	v_cvt_pk_f32_fp8_e32 v[40:41], v29
	v_pk_fma_f32 v[38:39], v[38:39], v[24:25], v[44:45] op_sel_hi:[1,0,1]
	v_pk_fma_f32 v[26:27], v[26:27], v[24:25], v[30:31] op_sel_hi:[1,0,1]
	v_cvt_pk_f32_fp8_e32 v[30:31], v28
	v_pk_fma_f32 v[40:41], v[40:41], v[24:25], v[46:47] op_sel_hi:[1,0,1]
	v_pk_fma_f32 v[30:31], v[30:31], v[24:25], v[34:35] op_sel_hi:[1,0,1]
	v_cvt_pk_f32_fp8_sdwa v[34:35], v28 src0_sel:WORD_1
	v_cvt_pk_f32_fp8_sdwa v[28:29], v29 src0_sel:WORD_1
	v_pk_fma_f32 v[34:35], v[34:35], v[24:25], v[42:43] op_sel_hi:[1,0,1]
	v_pk_fma_f32 v[22:23], v[28:29], v[24:25], v[22:23] op_sel_hi:[1,0,1]
	v_cvt_pk_f32_fp8_e32 v[28:29], v18
	v_mov_b32_e32 v24, v25
	v_pk_fma_f32 v[28:29], v[28:29], v[24:25], v[32:33] op_sel_hi:[1,0,1]
	v_cvt_pk_f32_fp8_sdwa v[32:33], v18 src0_sel:WORD_1
	v_pk_fma_f32 v[32:33], v[32:33], v[24:25], v[36:37] op_sel_hi:[1,0,1]
	v_cvt_pk_f32_fp8_e32 v[36:37], v19
	v_cvt_pk_f32_fp8_sdwa v[18:19], v19 src0_sel:WORD_1
	v_pk_fma_f32 v[36:37], v[36:37], v[24:25], v[38:39] op_sel_hi:[1,0,1]
	v_pk_fma_f32 v[18:19], v[18:19], v[24:25], v[26:27] op_sel_hi:[1,0,1]
	v_cvt_pk_f32_fp8_e32 v[26:27], v20
	v_pk_fma_f32 v[26:27], v[26:27], v[24:25], v[30:31] op_sel_hi:[1,0,1]
	v_cvt_pk_f32_fp8_sdwa v[30:31], v20 src0_sel:WORD_1
	s_nop 0
	v_permlane32_swap_b32_e32 v28, v26
	v_permlane32_swap_b32_e32 v29, v27
	v_pk_fma_f32 v[30:31], v[30:31], v[24:25], v[34:35] op_sel_hi:[1,0,1]
	v_cvt_pk_f32_fp8_e32 v[34:35], v21
	v_cvt_pk_f32_fp8_sdwa v[20:21], v21 src0_sel:WORD_1
	v_permlane32_swap_b32_e32 v32, v30
	v_pk_fma_f32 v[34:35], v[34:35], v[24:25], v[40:41] op_sel_hi:[1,0,1]
	v_pk_fma_f32 v[20:21], v[20:21], v[24:25], v[22:23] op_sel_hi:[1,0,1]
	v_permlane32_swap_b32_e32 v33, v31
	v_permlane32_swap_b32_e32 v36, v34
	v_permlane32_swap_b32_e32 v37, v35
	v_permlane32_swap_b32_e32 v18, v20
	v_permlane32_swap_b32_e32 v19, v21
	v_add_f32_e32 v22, v28, v26
	v_add_f32_e32 v23, v29, v27
	v_add_f32_e32 v24, v32, v30
	v_add_f32_e32 v25, v33, v31
	v_add_f32_e32 v26, v36, v34
	v_add_f32_e32 v27, v37, v35
	v_add_f32_e32 v18, v18, v20
	v_add_f32_e32 v19, v19, v21
	v_permlane16_swap_b32_e32 v22, v26
	v_permlane16_swap_b32_e32 v23, v27
	v_permlane16_swap_b32_e32 v24, v18
	v_permlane16_swap_b32_e32 v25, v19
	v_pk_add_f32 v[20:21], v[22:23], v[26:27]
	v_pk_add_f32 v[18:19], v[24:25], v[18:19]
	v_mov_b32_e32 v22, 0
	v_cndmask_b32_e32 v23, v20, v18, vcc
	v_cndmask_b32_e32 v24, v18, v20, vcc
	v_cndmask_b32_e32 v18, v21, v19, vcc
	v_mov_b32_dpp v22, v23 row_ror:8 row_mask:0xf bank_mask:0xf
	v_mov_b32_e32 v23, 0
	v_cndmask_b32_e32 v25, v19, v21, vcc
	v_lshl_add_u64 v[20:21], v[186:187], 0, s[12:13]
	v_mov_b32_dpp v23, v18 row_ror:8 row_mask:0xf bank_mask:0xf
	v_pk_add_f32 v[18:19], v[24:25], v[22:23]
	v_pk_add_f32 v[18:19], v[190:191], v[18:19]
	global_store_dwordx2 v[20:21], v[18:19], off
	s_mov_b32 s12, s14
	s_cbranch_scc0 .LBB0_1588
; __device__ __forceinline__ f32x2 fp8x2_lo(unsigned w) { return __builtin_amdgcn_cvt_pk_f32_fp8(w, false); }
; __device__ __forceinline__ f32x2 fp8x2_hi(unsigned w) { return __builtin_amdgcn_cvt_pk_f32_fp8(w, true); }
; #define PB_IDS(T) do { const unsigned* kp_ = KP + (size_t)(T) * 256; _Pragma("unroll") for (int qq = 0; qq < 4; ++qq) idv[qq] = *(const u32x4*)(kp_ + 4 * qq); } while (0)
; template <bool NT>
; __device__ __forceinline__ void peer_passB(const Args& a, const PeerWork w) {
;     ...
;     int t = peer_tok(w, q), t1 = peer_tok(w, min(q + qs, ql));
;     PB_IDS(t);
;     PB_GATHER(t, vr, cf, hv);
;     PB_IDS(t1);
; #pragma unroll 1
;     for (;; q += qs) {
;         u32x4 vrn[16]; f32x4 cfn[4]; f32x2 hn;
;         PB_GATHER(t1, vrn, cfn, hn);
;         const int t2 = peer_tok(w, min(q + 2 * qs, ql));
;         PB_IDS(t2);
;         f32x2 acc[8];
; #pragma unroll
;         for (int m = 0; m < 8; ++m) acc[m] = (f32x2){0.f, 0.f};
; #pragma unroll
;         for (int k = 0; k < 16; ++k) {
;             const unsigned ww[4] = {vr[k].x, vr[k].y, vr[k].z, vr[k].w};
;             const float c = cf[k >> 2][k & 3]; const f32x2 c2 = {c, c};
; #pragma unroll
;             for (int wd = 0; wd < 4; ++wd) { acc[2 * wd] = __builtin_elementwise_fma(fp8x2_lo(ww[wd]), c2, acc[2 * wd]); acc[2 * wd + 1] = __builtin_elementwise_fma(fp8x2_hi(ww[wd]), c2, acc[2 * wd + 1]); }
	s_waitcnt vmcnt(23)
	v_cvt_pk_f32_fp8_e32 v[192:193], v70
	s_waitcnt vmcnt(19)
	v_cvt_pk_f32_fp8_e32 v[204:205], v74
	v_cvt_pk_f32_fp8_sdwa v[194:195], v70 src0_sel:WORD_1
	v_cvt_pk_f32_fp8_e32 v[196:197], v71
	s_waitcnt vmcnt(6)
	v_pk_fma_f32 v[192:193], v[192:193], v[154:155], 0 op_sel_hi:[1,0,0]
	v_cvt_pk_f32_fp8_sdwa v[70:71], v71 src0_sel:WORD_1
	v_pk_fma_f32 v[192:193], v[204:205], v[154:155], v[192:193] op_sel:[0,1,0]
	v_cvt_pk_f32_fp8_sdwa v[204:205], v74 src0_sel:WORD_1
	v_pk_fma_f32 v[194:195], v[194:195], v[154:155], 0 op_sel_hi:[1,0,0]
	v_pk_fma_f32 v[70:71], v[70:71], v[154:155], 0 op_sel_hi:[1,0,0]
	v_cvt_pk_f32_fp8_e32 v[198:199], v72
	v_pk_fma_f32 v[194:195], v[204:205], v[154:155], v[194:195] op_sel:[0,1,0]
	v_cvt_pk_f32_fp8_e32 v[204:205], v75
	v_cvt_pk_f32_fp8_sdwa v[74:75], v75 src0_sel:WORD_1
	v_pk_fma_f32 v[198:199], v[198:199], v[154:155], 0 op_sel_hi:[1,0,0]
	v_cvt_pk_f32_fp8_sdwa v[200:201], v72 src0_sel:WORD_1
	v_cvt_pk_f32_fp8_e32 v[202:203], v73
	v_pk_fma_f32 v[74:75], v[74:75], v[154:155], v[70:71] op_sel:[0,1,0]
	v_cvt_pk_f32_fp8_e32 v[70:71], v76
	v_pk_fma_f32 v[200:201], v[200:201], v[154:155], 0 op_sel_hi:[1,0,0]
	v_cvt_pk_f32_fp8_sdwa v[72:73], v73 src0_sel:WORD_1
	v_pk_fma_f32 v[196:197], v[196:197], v[154:155], 0 op_sel_hi:[1,0,0]
	v_pk_fma_f32 v[70:71], v[70:71], v[154:155], v[198:199] op_sel:[0,1,0]
	v_cvt_pk_f32_fp8_sdwa v[198:199], v76 src0_sel:WORD_1
	v_pk_fma_f32 v[202:203], v[202:203], v[154:155], 0 op_sel_hi:[1,0,0]
	v_pk_fma_f32 v[72:73], v[72:73], v[154:155], 0 op_sel_hi:[1,0,0]
	v_pk_fma_f32 v[196:197], v[204:205], v[154:155], v[196:197] op_sel:[0,1,0]
	v_pk_fma_f32 v[198:199], v[198:199], v[154:155], v[200:201] op_sel:[0,1,0]
	v_cvt_pk_f32_fp8_e32 v[200:201], v77
	v_cvt_pk_f32_fp8_sdwa v[76:77], v77 src0_sel:WORD_1
	s_waitcnt vmcnt(3)
	v_lshl_or_b32 v6, v6, 7, v1
	v_lshl_or_b32 v2, v2, 7, v1
	v_pk_fma_f32 v[200:201], v[200:201], v[154:155], v[202:203] op_sel:[0,1,0]
	v_pk_fma_f32 v[154:155], v[76:77], v[154:155], v[72:73] op_sel:[0,1,0]
	v_cvt_pk_f32_fp8_e32 v[76:77], v78
	v_cvt_pk_f32_fp8_sdwa v[72:73], v78 src0_sel:WORD_1
	s_waitcnt vmcnt(1)
	v_lshl_or_b32 v14, v14, 7, v1
	v_lshl_or_b32 v10, v10, 7, v1
	v_pk_fma_f32 v[76:77], v[76:77], v[156:157], v[192:193] op_sel_hi:[1,0,1]
	v_cvt_pk_f32_fp8_e32 v[192:193], v79
	v_cvt_pk_f32_fp8_sdwa v[78:79], v79 src0_sel:WORD_1
	v_pk_fma_f32 v[72:73], v[72:73], v[156:157], v[194:195] op_sel_hi:[1,0,1]
	v_cvt_pk_f32_fp8_e32 v[194:195], v81
	v_pk_fma_f32 v[192:193], v[192:193], v[156:157], v[196:197] op_sel_hi:[1,0,1]
	v_pk_fma_f32 v[78:79], v[78:79], v[156:157], v[74:75] op_sel_hi:[1,0,1]
	v_cvt_pk_f32_fp8_e32 v[74:75], v80
	v_pk_fma_f32 v[194:195], v[194:195], v[156:157], v[200:201] op_sel_hi:[1,0,1]
	global_load_dwordx4 v[54:57], v6, s[4:5]
	global_load_dwordx4 v[34:37], v2, s[4:5]
	v_pk_fma_f32 v[74:75], v[74:75], v[156:157], v[70:71] op_sel_hi:[1,0,1]
	v_cvt_pk_f32_fp8_sdwa v[70:71], v80 src0_sel:WORD_1
	v_cvt_pk_f32_fp8_sdwa v[80:81], v81 src0_sel:WORD_1
	v_lshl_or_b32 v6, v7, 7, v1
	v_lshl_or_b32 v2, v3, 7, v1
	v_pk_fma_f32 v[70:71], v[70:71], v[156:157], v[198:199] op_sel_hi:[1,0,1]
	v_pk_fma_f32 v[154:155], v[80:81], v[156:157], v[154:155] op_sel_hi:[1,0,1]
	v_cvt_pk_f32_fp8_e32 v[80:81], v82
	v_mov_b32_e32 v156, v157
	s_mov_b32 s14, s6
	global_load_dwordx4 v[174:177], v14, s[4:5]
	global_load_dwordx4 v[138:141], v10, s[4:5]
	v_pk_fma_f32 v[80:81], v[80:81], v[156:157], v[76:77] op_sel_hi:[1,0,1]
	v_cvt_pk_f32_fp8_sdwa v[76:77], v82 src0_sel:WORD_1
	v_lshl_or_b32 v14, v15, 7, v1
	v_lshl_or_b32 v10, v11, 7, v1
	global_load_dwordx4 v[50:53], v6, s[4:5]
	global_load_dwordx4 v[30:33], v2, s[4:5]
	v_pk_fma_f32 v[76:77], v[76:77], v[156:157], v[72:73] op_sel_hi:[1,0,1]
	v_cvt_pk_f32_fp8_e32 v[72:73], v83
	v_cvt_pk_f32_fp8_sdwa v[82:83], v83 src0_sel:WORD_1
	v_lshl_or_b32 v6, v8, 7, v1
	v_lshl_or_b32 v2, v4, 7, v1
	v_pk_fma_f32 v[72:73], v[72:73], v[156:157], v[192:193] op_sel_hi:[1,0,1]
	v_pk_fma_f32 v[82:83], v[82:83], v[156:157], v[78:79] op_sel_hi:[1,0,1]
	v_cvt_pk_f32_fp8_e32 v[78:79], v84
	s_ashr_i32 s15, s6, 31
	global_load_dwordx4 v[170:173], v14, s[4:5]
	global_load_dwordx4 v[94:97], v10, s[4:5]
	v_pk_fma_f32 v[78:79], v[78:79], v[156:157], v[74:75] op_sel_hi:[1,0,1]
	v_cvt_pk_f32_fp8_sdwa v[74:75], v84 src0_sel:WORD_1
	v_lshl_or_b32 v14, v16, 7, v1
	v_lshl_or_b32 v10, v12, 7, v1
	global_load_dwordx4 v[46:49], v6, s[4:5]
	global_load_dwordx4 v[26:29], v2, s[4:5]
	v_pk_fma_f32 v[74:75], v[74:75], v[156:157], v[70:71] op_sel_hi:[1,0,1]
	v_cvt_pk_f32_fp8_e32 v[70:71], v85
	v_cvt_pk_f32_fp8_sdwa v[84:85], v85 src0_sel:WORD_1
	v_lshl_or_b32 v6, v9, 7, v1
	v_lshl_or_b32 v2, v5, 7, v1
	v_pk_fma_f32 v[70:71], v[70:71], v[156:157], v[194:195] op_sel_hi:[1,0,1]
	v_pk_fma_f32 v[84:85], v[84:85], v[156:157], v[154:155] op_sel_hi:[1,0,1]
	v_cvt_pk_f32_fp8_e32 v[154:155], v86
	v_cvt_pk_f32_fp8_sdwa v[156:157], v86 src0_sel:WORD_1
	s_lshl_b64 s[6:7], s[14:15], 9
	global_load_dwordx4 v[166:169], v14, s[4:5]
	global_load_dwordx4 v[66:69], v10, s[4:5]
	v_pk_fma_f32 v[154:155], v[154:155], v[150:151], v[80:81] op_sel_hi:[1,0,1]
	v_cvt_pk_f32_fp8_e32 v[80:81], v87
	v_cvt_pk_f32_fp8_sdwa v[86:87], v87 src0_sel:WORD_1
	v_pk_fma_f32 v[156:157], v[156:157], v[150:151], v[76:77] op_sel_hi:[1,0,1]
	v_lshl_or_b32 v14, v17, 7, v1
	v_pk_fma_f32 v[80:81], v[80:81], v[150:151], v[72:73] op_sel_hi:[1,0,1]
	v_pk_fma_f32 v[86:87], v[86:87], v[150:151], v[82:83] op_sel_hi:[1,0,1]
	v_cvt_pk_f32_fp8_e32 v[82:83], v88
	v_lshl_or_b32 v10, v13, 7, v1
	global_load_dwordx4 v[42:45], v6, s[4:5]
	global_load_dwordx4 v[18:21], v2, s[4:5]
	v_pk_fma_f32 v[82:83], v[82:83], v[150:151], v[78:79] op_sel_hi:[1,0,1]
; __device__ __forceinline__ f32x2 fp8x2_lo(unsigned w) { return __builtin_amdgcn_cvt_pk_f32_fp8(w, false); }
; __device__ __forceinline__ f32x2 fp8x2_hi(unsigned w) { return __builtin_amdgcn_cvt_pk_f32_fp8(w, true); }
; #define PB_IDS(T) do { const unsigned* kp_ = KP + (size_t)(T) * 256; _Pragma("unroll") for (int qq = 0; qq < 4; ++qq) idv[qq] = *(const u32x4*)(kp_ + 4 * qq); } while (0)
; template <bool NT>
; __device__ __forceinline__ void peer_passB(const Args& a, const PeerWork w) {
;     ...
;     int t = peer_tok(w, q), t1 = peer_tok(w, min(q + qs, ql));
;     PB_IDS(t);
;     PB_GATHER(t, vr, cf, hv);
;     PB_IDS(t1);
; #pragma unroll 1
;     for (;; q += qs) {
;         u32x4 vrn[16]; f32x4 cfn[4]; f32x2 hn;
;         PB_GATHER(t1, vrn, cfn, hn);
;         const int t2 = peer_tok(w, min(q + 2 * qs, ql));
;         PB_IDS(t2);
;         f32x2 acc[8];
; #pragma unroll
;         for (int m = 0; m < 8; ++m) acc[m] = (f32x2){0.f, 0.f};
; #pragma unroll
;         for (int k = 0; k < 16; ++k) {
;             const unsigned ww[4] = {vr[k].x, vr[k].y, vr[k].z, vr[k].w};
;             const float c = cf[k >> 2][k & 3]; const f32x2 c2 = {c, c};
; #pragma unroll
;             for (int wd = 0; wd < 4; ++wd) { acc[2 * wd] = __builtin_elementwise_fma(fp8x2_lo(ww[wd]), c2, acc[2 * wd]); acc[2 * wd + 1] = __builtin_elementwise_fma(fp8x2_hi(ww[wd]), c2, acc[2 * wd + 1]); }
;         }
	v_cvt_pk_f32_fp8_sdwa v[78:79], v88 src0_sel:WORD_1
	v_lshl_add_u64 v[2:3], v[184:185], 0, s[6:7]
	s_lshl_b64 s[6:7], s[14:15], 12
	global_load_dwordx4 v[158:161], v14, s[4:5]
	global_load_dwordx4 v[58:61], v10, s[4:5]
	v_pk_fma_f32 v[78:79], v[78:79], v[150:151], v[74:75] op_sel_hi:[1,0,1]
	v_cvt_pk_f32_fp8_e32 v[74:75], v89
	v_cvt_pk_f32_fp8_sdwa v[88:89], v89 src0_sel:WORD_1
	global_load_dwordx4 v[22:25], v[2:3], off offset:48
	global_load_dwordx4 v[38:41], v[2:3], off offset:32
	global_load_dwordx4 v[62:65], v[2:3], off offset:16
	global_load_dwordx4 v[162:165], v[2:3], off
	v_lshl_add_u64 v[2:3], v[182:183], 0, s[6:7]
	v_pk_fma_f32 v[74:75], v[74:75], v[150:151], v[70:71] op_sel_hi:[1,0,1]
	v_pk_fma_f32 v[88:89], v[88:89], v[150:151], v[84:85] op_sel_hi:[1,0,1]
	v_cvt_pk_f32_fp8_e32 v[84:85], v90
	s_add_i32 s6, s11, s18
	s_min_i32 s6, s6, 0x3fff
	s_ashr_i32 s7, s6, 31
	v_pk_fma_f32 v[84:85], v[84:85], v[150:151], v[154:155] op_sel:[0,1,0]
	v_cvt_pk_f32_fp8_sdwa v[154:155], v90 src0_sel:WORD_1
	s_lshl_b64 s[28:29], s[6:7], 10
	v_lshl_add_u64 v[14:15], v[180:181], 0, s[28:29]
	global_load_dwordx2 v[190:191], v[2:3], off
	v_pk_fma_f32 v[154:155], v[154:155], v[150:151], v[156:157] op_sel:[0,1,0]
	v_cvt_pk_f32_fp8_e32 v[156:157], v91
	v_cvt_pk_f32_fp8_sdwa v[90:91], v91 src0_sel:WORD_1
	global_load_dwordx4 v[2:5], v[14:15], off offset:48
	global_load_dwordx4 v[6:9], v[14:15], off offset:32
	global_load_dwordx4 v[10:13], v[14:15], off offset:16
	s_nop 0
	global_load_dwordx4 v[14:17], v[14:15], off
	s_ashr_i32 s13, s12, 31
	v_pk_fma_f32 v[156:157], v[156:157], v[150:151], v[80:81] op_sel:[0,1,0]
	v_pk_fma_f32 v[90:91], v[90:91], v[150:151], v[86:87] op_sel:[0,1,0]
	v_cvt_pk_f32_fp8_e32 v[86:87], v92
	s_lshl_b64 s[12:13], s[12:13], 12
	s_add_i32 s18, s18, s22
	v_pk_fma_f32 v[86:87], v[86:87], v[150:151], v[82:83] op_sel:[0,1,0]
	v_cvt_pk_f32_fp8_sdwa v[82:83], v92 src0_sel:WORD_1
	s_cmpk_lt_i32 s18, 0x4000
	v_pk_fma_f32 v[82:83], v[82:83], v[150:151], v[78:79] op_sel:[0,1,0]
	v_cvt_pk_f32_fp8_e32 v[78:79], v93
	v_cvt_pk_f32_fp8_sdwa v[92:93], v93 src0_sel:WORD_1
	v_pk_fma_f32 v[78:79], v[78:79], v[150:151], v[74:75] op_sel:[0,1,0]
	v_pk_fma_f32 v[150:151], v[92:93], v[150:151], v[88:89] op_sel:[0,1,0]
	v_cvt_pk_f32_fp8_e32 v[92:93], v98
	v_cvt_pk_f32_fp8_sdwa v[88:89], v98 src0_sel:WORD_1
	v_pk_fma_f32 v[92:93], v[92:93], v[152:153], v[84:85] op_sel_hi:[1,0,1]
	v_cvt_pk_f32_fp8_e32 v[84:85], v99
	v_cvt_pk_f32_fp8_sdwa v[98:99], v99 src0_sel:WORD_1
	v_pk_fma_f32 v[88:89], v[88:89], v[152:153], v[154:155] op_sel_hi:[1,0,1]
	v_pk_fma_f32 v[84:85], v[84:85], v[152:153], v[156:157] op_sel_hi:[1,0,1]
	v_pk_fma_f32 v[98:99], v[98:99], v[152:153], v[90:91] op_sel_hi:[1,0,1]
	v_cvt_pk_f32_fp8_e32 v[90:91], v100
	v_pk_fma_f32 v[90:91], v[90:91], v[152:153], v[86:87] op_sel_hi:[1,0,1]
	v_cvt_pk_f32_fp8_sdwa v[86:87], v100 src0_sel:WORD_1
	v_pk_fma_f32 v[86:87], v[86:87], v[152:153], v[82:83] op_sel_hi:[1,0,1]
	v_cvt_pk_f32_fp8_e32 v[82:83], v101
	v_cvt_pk_f32_fp8_sdwa v[100:101], v101 src0_sel:WORD_1
	v_pk_fma_f32 v[82:83], v[82:83], v[152:153], v[78:79] op_sel_hi:[1,0,1]
	v_pk_fma_f32 v[150:151], v[100:101], v[152:153], v[150:151] op_sel_hi:[1,0,1]
	v_cvt_pk_f32_fp8_e32 v[100:101], v102
	v_mov_b32_e32 v152, v153
	v_pk_fma_f32 v[100:101], v[100:101], v[152:153], v[92:93] op_sel_hi:[1,0,1]
	v_cvt_pk_f32_fp8_sdwa v[92:93], v102 src0_sel:WORD_1
	v_pk_fma_f32 v[92:93], v[92:93], v[152:153], v[88:89] op_sel_hi:[1,0,1]
	v_cvt_pk_f32_fp8_e32 v[88:89], v103
	v_cvt_pk_f32_fp8_sdwa v[102:103], v103 src0_sel:WORD_1
	v_pk_fma_f32 v[88:89], v[88:89], v[152:153], v[84:85] op_sel_hi:[1,0,1]
	v_pk_fma_f32 v[102:103], v[102:103], v[152:153], v[98:99] op_sel_hi:[1,0,1]
	v_cvt_pk_f32_fp8_e32 v[98:99], v104
	v_pk_fma_f32 v[98:99], v[98:99], v[152:153], v[90:91] op_sel_hi:[1,0,1]
	v_cvt_pk_f32_fp8_sdwa v[90:91], v104 src0_sel:WORD_1
	v_pk_fma_f32 v[90:91], v[90:91], v[152:153], v[86:87] op_sel_hi:[1,0,1]
	v_cvt_pk_f32_fp8_e32 v[86:87], v105
	v_cvt_pk_f32_fp8_sdwa v[104:105], v105 src0_sel:WORD_1
	v_pk_fma_f32 v[86:87], v[86:87], v[152:153], v[82:83] op_sel_hi:[1,0,1]
	v_pk_fma_f32 v[104:105], v[104:105], v[152:153], v[150:151] op_sel_hi:[1,0,1]
	v_cvt_pk_f32_fp8_e32 v[150:151], v106
	v_cvt_pk_f32_fp8_sdwa v[152:153], v106 src0_sel:WORD_1
	v_pk_fma_f32 v[150:151], v[150:151], v[146:147], v[100:101] op_sel_hi:[1,0,1]
	v_cvt_pk_f32_fp8_e32 v[100:101], v107
	v_cvt_pk_f32_fp8_sdwa v[106:107], v107 src0_sel:WORD_1
	v_pk_fma_f32 v[152:153], v[152:153], v[146:147], v[92:93] op_sel_hi:[1,0,1]
	v_pk_fma_f32 v[100:101], v[100:101], v[146:147], v[88:89] op_sel_hi:[1,0,1]
	v_pk_fma_f32 v[106:107], v[106:107], v[146:147], v[102:103] op_sel_hi:[1,0,1]
	v_cvt_pk_f32_fp8_e32 v[102:103], v108
	v_pk_fma_f32 v[102:103], v[102:103], v[146:147], v[98:99] op_sel_hi:[1,0,1]
	v_cvt_pk_f32_fp8_sdwa v[98:99], v108 src0_sel:WORD_1
	v_pk_fma_f32 v[98:99], v[98:99], v[146:147], v[90:91] op_sel_hi:[1,0,1]
	v_cvt_pk_f32_fp8_e32 v[90:91], v109
	v_cvt_pk_f32_fp8_sdwa v[108:109], v109 src0_sel:WORD_1
	v_pk_fma_f32 v[90:91], v[90:91], v[146:147], v[86:87] op_sel_hi:[1,0,1]
	v_pk_fma_f32 v[108:109], v[108:109], v[146:147], v[104:105] op_sel_hi:[1,0,1]
	v_cvt_pk_f32_fp8_e32 v[104:105], v110
	v_pk_fma_f32 v[104:105], v[104:105], v[146:147], v[150:151] op_sel:[0,1,0]
	v_cvt_pk_f32_fp8_sdwa v[150:151], v110 src0_sel:WORD_1
	v_pk_fma_f32 v[150:151], v[150:151], v[146:147], v[152:153] op_sel:[0,1,0]
	v_cvt_pk_f32_fp8_e32 v[152:153], v111
	v_cvt_pk_f32_fp8_sdwa v[110:111], v111 src0_sel:WORD_1
	v_pk_fma_f32 v[152:153], v[152:153], v[146:147], v[100:101] op_sel:[0,1,0]
	v_pk_fma_f32 v[110:111], v[110:111], v[146:147], v[106:107] op_sel:[0,1,0]
; __device__ __forceinline__ f32x2 fp8x2_lo(unsigned w) { return __builtin_amdgcn_cvt_pk_f32_fp8(w, false); }
; __device__ __forceinline__ f32x2 fp8x2_hi(unsigned w) { return __builtin_amdgcn_cvt_pk_f32_fp8(w, true); }
; template <bool NT>
; __device__ __forceinline__ void peer_passB(const Args& a, const PeerWork w) {
;     ...
;         for (int k = 0; k < 16; ++k) {
;             const unsigned ww[4] = {vr[k].x, vr[k].y, vr[k].z, vr[k].w};
;             const float c = cf[k >> 2][k & 3]; const f32x2 c2 = {c, c};
; #pragma unroll
;             for (int wd = 0; wd < 4; ++wd) { acc[2 * wd] = __builtin_elementwise_fma(fp8x2_lo(ww[wd]), c2, acc[2 * wd]); acc[2 * wd + 1] = __builtin_elementwise_fma(fp8x2_hi(ww[wd]), c2, acc[2 * wd + 1]); }
;         }
	v_cvt_pk_f32_fp8_e32 v[106:107], v112
	v_pk_fma_f32 v[106:107], v[106:107], v[146:147], v[102:103] op_sel:[0,1,0]
	v_cvt_pk_f32_fp8_sdwa v[102:103], v112 src0_sel:WORD_1
	v_pk_fma_f32 v[102:103], v[102:103], v[146:147], v[98:99] op_sel:[0,1,0]
	v_cvt_pk_f32_fp8_e32 v[98:99], v113
	v_cvt_pk_f32_fp8_sdwa v[112:113], v113 src0_sel:WORD_1
	v_pk_fma_f32 v[98:99], v[98:99], v[146:147], v[90:91] op_sel:[0,1,0]
	v_pk_fma_f32 v[146:147], v[112:113], v[146:147], v[108:109] op_sel:[0,1,0]
	v_cvt_pk_f32_fp8_e32 v[112:113], v114
	v_cvt_pk_f32_fp8_sdwa v[108:109], v114 src0_sel:WORD_1
	v_pk_fma_f32 v[112:113], v[112:113], v[148:149], v[104:105] op_sel_hi:[1,0,1]
	v_cvt_pk_f32_fp8_e32 v[104:105], v115
	v_cvt_pk_f32_fp8_sdwa v[114:115], v115 src0_sel:WORD_1
	v_pk_fma_f32 v[108:109], v[108:109], v[148:149], v[150:151] op_sel_hi:[1,0,1]
	v_pk_fma_f32 v[104:105], v[104:105], v[148:149], v[152:153] op_sel_hi:[1,0,1]
	v_pk_fma_f32 v[114:115], v[114:115], v[148:149], v[110:111] op_sel_hi:[1,0,1]
	v_cvt_pk_f32_fp8_e32 v[110:111], v116
	v_pk_fma_f32 v[110:111], v[110:111], v[148:149], v[106:107] op_sel_hi:[1,0,1]
	v_cvt_pk_f32_fp8_sdwa v[106:107], v116 src0_sel:WORD_1
	v_pk_fma_f32 v[106:107], v[106:107], v[148:149], v[102:103] op_sel_hi:[1,0,1]
	v_cvt_pk_f32_fp8_e32 v[102:103], v117
	v_cvt_pk_f32_fp8_sdwa v[116:117], v117 src0_sel:WORD_1
	v_pk_fma_f32 v[102:103], v[102:103], v[148:149], v[98:99] op_sel_hi:[1,0,1]
	v_pk_fma_f32 v[146:147], v[116:117], v[148:149], v[146:147] op_sel_hi:[1,0,1]
	v_cvt_pk_f32_fp8_e32 v[116:117], v118
	v_mov_b32_e32 v148, v149
	v_pk_fma_f32 v[116:117], v[116:117], v[148:149], v[112:113] op_sel_hi:[1,0,1]
	v_cvt_pk_f32_fp8_sdwa v[112:113], v118 src0_sel:WORD_1
	v_pk_fma_f32 v[112:113], v[112:113], v[148:149], v[108:109] op_sel_hi:[1,0,1]
	v_cvt_pk_f32_fp8_e32 v[108:109], v119
	v_cvt_pk_f32_fp8_sdwa v[118:119], v119 src0_sel:WORD_1
	v_pk_fma_f32 v[108:109], v[108:109], v[148:149], v[104:105] op_sel_hi:[1,0,1]
	v_pk_fma_f32 v[118:119], v[118:119], v[148:149], v[114:115] op_sel_hi:[1,0,1]
	v_cvt_pk_f32_fp8_e32 v[114:115], v120
	v_pk_fma_f32 v[114:115], v[114:115], v[148:149], v[110:111] op_sel_hi:[1,0,1]
	v_cvt_pk_f32_fp8_sdwa v[110:111], v120 src0_sel:WORD_1
	v_pk_fma_f32 v[110:111], v[110:111], v[148:149], v[106:107] op_sel_hi:[1,0,1]
	v_cvt_pk_f32_fp8_e32 v[106:107], v121
	v_cvt_pk_f32_fp8_sdwa v[120:121], v121 src0_sel:WORD_1
	v_pk_fma_f32 v[106:107], v[106:107], v[148:149], v[102:103] op_sel_hi:[1,0,1]
	v_pk_fma_f32 v[146:147], v[120:121], v[148:149], v[146:147] op_sel_hi:[1,0,1]
	v_cvt_pk_f32_fp8_e32 v[148:149], v122
	v_cvt_pk_f32_fp8_sdwa v[120:121], v122 src0_sel:WORD_1
	v_pk_fma_f32 v[148:149], v[148:149], v[142:143], v[116:117] op_sel_hi:[1,0,1]
	v_cvt_pk_f32_fp8_e32 v[116:117], v123
	v_cvt_pk_f32_fp8_sdwa v[122:123], v123 src0_sel:WORD_1
	v_pk_fma_f32 v[120:121], v[120:121], v[142:143], v[112:113] op_sel_hi:[1,0,1]
	v_pk_fma_f32 v[116:117], v[116:117], v[142:143], v[108:109] op_sel_hi:[1,0,1]
	v_pk_fma_f32 v[122:123], v[122:123], v[142:143], v[118:119] op_sel_hi:[1,0,1]
	v_cvt_pk_f32_fp8_e32 v[118:119], v124
	v_pk_fma_f32 v[118:119], v[118:119], v[142:143], v[114:115] op_sel_hi:[1,0,1]
	v_cvt_pk_f32_fp8_sdwa v[114:115], v124 src0_sel:WORD_1
	v_pk_fma_f32 v[114:115], v[114:115], v[142:143], v[110:111] op_sel_hi:[1,0,1]
	v_cvt_pk_f32_fp8_e32 v[110:111], v125
	v_cvt_pk_f32_fp8_sdwa v[124:125], v125 src0_sel:WORD_1
	v_pk_fma_f32 v[110:111], v[110:111], v[142:143], v[106:107] op_sel_hi:[1,0,1]
	v_pk_fma_f32 v[124:125], v[124:125], v[142:143], v[146:147] op_sel_hi:[1,0,1]
	v_cvt_pk_f32_fp8_e32 v[146:147], v126
	v_pk_fma_f32 v[146:147], v[146:147], v[142:143], v[148:149] op_sel:[0,1,0]
	v_cvt_pk_f32_fp8_sdwa v[148:149], v126 src0_sel:WORD_1
	v_pk_fma_f32 v[148:149], v[148:149], v[142:143], v[120:121] op_sel:[0,1,0]
	v_cvt_pk_f32_fp8_e32 v[120:121], v127
	v_cvt_pk_f32_fp8_sdwa v[126:127], v127 src0_sel:WORD_1
	v_pk_fma_f32 v[120:121], v[120:121], v[142:143], v[116:117] op_sel:[0,1,0]
	v_pk_fma_f32 v[126:127], v[126:127], v[142:143], v[122:123] op_sel:[0,1,0]
; template <int CTRL> __device__ __forceinline__ float dpp_f(float x) { return __uint_as_float((unsigned)__builtin_amdgcn_update_dpp(0, (int)__float_as_uint(x), CTRL, 0xf, 0xf, false)); }
; __device__ __forceinline__ f32x2 fp8x2_lo(unsigned w) { return __builtin_amdgcn_cvt_pk_f32_fp8(w, false); }
; __device__ __forceinline__ f32x2 fp8x2_hi(unsigned w) { return __builtin_amdgcn_cvt_pk_f32_fp8(w, true); }
; template <bool NT>
; __device__ __forceinline__ void peer_passB(const Args& a, const PeerWork w) {
;     ...
;         for (int k = 0; k < 16; ++k) {
;             const unsigned ww[4] = {vr[k].x, vr[k].y, vr[k].z, vr[k].w};
;             const float c = cf[k >> 2][k & 3]; const f32x2 c2 = {c, c};
; #pragma unroll
;             for (int wd = 0; wd < 4; ++wd) { acc[2 * wd] = __builtin_elementwise_fma(fp8x2_lo(ww[wd]), c2, acc[2 * wd]); acc[2 * wd + 1] = __builtin_elementwise_fma(fp8x2_hi(ww[wd]), c2, acc[2 * wd + 1]); }
;         }
;         float w8[8], w4[4], w2[2];
; #pragma unroll
;         for (int m = 0; m < 8; ++m) { const auto sw = __builtin_amdgcn_permlane32_swap(__float_as_uint(acc[m >> 1][m & 1]), __float_as_uint(acc[(m + 8) >> 1][m & 1]), false, false); w8[m] = __uint_as_float(sw[0]) + __uint_as_float(sw[1]); }
; #pragma unroll
;         for (int m = 0; m < 4; ++m) { const auto sw = __builtin_amdgcn_permlane16_swap(__float_as_uint(w8[m]), __float_as_uint(w8[m + 4]), false, false); w4[m] = __uint_as_float(sw[0]) + __uint_as_float(sw[1]); }
;         { const bool up = (lane & 8) != 0;
; #pragma unroll
;           for (int m = 0; m < 2; ++m) { const float keep = up ? w4[m + 2] : w4[m], send = up ? w4[m] : w4[m + 2]; w2[m] = keep + dpp_f<0x128>(send); } }
;         *(f32x2*)(Y + (size_t)t * DM) = (f32x2){hv[0] + w2[0], hv[1] + w2[1]};
;         if (q + qs > ql) break;
; #pragma unroll
;         for (int k = 0; k < 16; ++k) vr[k] = vrn[k];
; #pragma unroll
;         for (int qq = 0; qq < 4; ++qq) cf[qq] = cfn[qq];
;         hv = hn;
;         t = t1; t1 = t2;
;     }
	v_cvt_pk_f32_fp8_e32 v[122:123], v128
	v_pk_fma_f32 v[122:123], v[122:123], v[142:143], v[118:119] op_sel:[0,1,0]
	v_cvt_pk_f32_fp8_sdwa v[118:119], v128 src0_sel:WORD_1
	v_pk_fma_f32 v[118:119], v[118:119], v[142:143], v[114:115] op_sel:[0,1,0]
	v_cvt_pk_f32_fp8_e32 v[114:115], v129
	v_cvt_pk_f32_fp8_sdwa v[128:129], v129 src0_sel:WORD_1
	v_pk_fma_f32 v[114:115], v[114:115], v[142:143], v[110:111] op_sel:[0,1,0]
	v_pk_fma_f32 v[142:143], v[128:129], v[142:143], v[124:125] op_sel:[0,1,0]
	v_cvt_pk_f32_fp8_e32 v[128:129], v130
	v_cvt_pk_f32_fp8_sdwa v[124:125], v130 src0_sel:WORD_1
	v_pk_fma_f32 v[128:129], v[128:129], v[144:145], v[146:147] op_sel_hi:[1,0,1]
	v_cvt_pk_f32_fp8_e32 v[146:147], v131
	v_cvt_pk_f32_fp8_sdwa v[130:131], v131 src0_sel:WORD_1
	v_pk_fma_f32 v[124:125], v[124:125], v[144:145], v[148:149] op_sel_hi:[1,0,1]
	v_cvt_pk_f32_fp8_e32 v[148:149], v133
	v_pk_fma_f32 v[146:147], v[146:147], v[144:145], v[120:121] op_sel_hi:[1,0,1]
	v_pk_fma_f32 v[130:131], v[130:131], v[144:145], v[126:127] op_sel_hi:[1,0,1]
	v_cvt_pk_f32_fp8_e32 v[126:127], v132
	v_pk_fma_f32 v[148:149], v[148:149], v[144:145], v[114:115] op_sel_hi:[1,0,1]
	v_pk_fma_f32 v[126:127], v[126:127], v[144:145], v[122:123] op_sel_hi:[1,0,1]
	v_cvt_pk_f32_fp8_sdwa v[122:123], v132 src0_sel:WORD_1
	v_cvt_pk_f32_fp8_sdwa v[132:133], v133 src0_sel:WORD_1
	v_pk_fma_f32 v[122:123], v[122:123], v[144:145], v[118:119] op_sel_hi:[1,0,1]
	v_pk_fma_f32 v[142:143], v[132:133], v[144:145], v[142:143] op_sel_hi:[1,0,1]
	v_cvt_pk_f32_fp8_e32 v[132:133], v134
	v_mov_b32_e32 v144, v145
	v_pk_fma_f32 v[132:133], v[132:133], v[144:145], v[128:129] op_sel_hi:[1,0,1]
	v_cvt_pk_f32_fp8_sdwa v[128:129], v134 src0_sel:WORD_1
	v_pk_fma_f32 v[128:129], v[128:129], v[144:145], v[124:125] op_sel_hi:[1,0,1]
	v_cvt_pk_f32_fp8_e32 v[124:125], v135
	v_cvt_pk_f32_fp8_sdwa v[134:135], v135 src0_sel:WORD_1
	v_pk_fma_f32 v[124:125], v[124:125], v[144:145], v[146:147] op_sel_hi:[1,0,1]
	v_pk_fma_f32 v[134:135], v[134:135], v[144:145], v[130:131] op_sel_hi:[1,0,1]
	v_cvt_pk_f32_fp8_e32 v[130:131], v136
	v_pk_fma_f32 v[130:131], v[130:131], v[144:145], v[126:127] op_sel_hi:[1,0,1]
	v_cvt_pk_f32_fp8_sdwa v[126:127], v136 src0_sel:WORD_1
	s_nop 0
	v_permlane32_swap_b32_e32 v132, v130
	v_permlane32_swap_b32_e32 v133, v131
	v_pk_fma_f32 v[126:127], v[126:127], v[144:145], v[122:123] op_sel_hi:[1,0,1]
	v_cvt_pk_f32_fp8_e32 v[122:123], v137
	v_cvt_pk_f32_fp8_sdwa v[136:137], v137 src0_sel:WORD_1
	v_permlane32_swap_b32_e32 v128, v126
	v_pk_fma_f32 v[122:123], v[122:123], v[144:145], v[148:149] op_sel_hi:[1,0,1]
	v_pk_fma_f32 v[136:137], v[136:137], v[144:145], v[142:143] op_sel_hi:[1,0,1]
	v_permlane32_swap_b32_e32 v129, v127
	v_permlane32_swap_b32_e32 v124, v122
	v_permlane32_swap_b32_e32 v125, v123
	v_permlane32_swap_b32_e32 v134, v136
	v_permlane32_swap_b32_e32 v135, v137
	v_add_f32_e32 v142, v132, v130
	v_add_f32_e32 v143, v133, v131
	v_add_f32_e32 v144, v128, v126
	v_add_f32_e32 v145, v129, v127
	v_add_f32_e32 v130, v124, v122
	v_add_f32_e32 v131, v125, v123
	v_add_f32_e32 v134, v134, v136
	v_add_f32_e32 v135, v135, v137
	v_permlane16_swap_b32_e32 v142, v130
	v_permlane16_swap_b32_e32 v143, v131
	v_permlane16_swap_b32_e32 v144, v134
	v_permlane16_swap_b32_e32 v145, v135
	v_pk_add_f32 v[136:137], v[142:143], v[130:131]
	v_pk_add_f32 v[134:135], v[144:145], v[134:135]
	v_mov_b32_e32 v142, 0
	v_cndmask_b32_e32 v143, v136, v134, vcc
	v_cndmask_b32_e32 v144, v134, v136, vcc
	v_cndmask_b32_e32 v134, v137, v135, vcc
	v_mov_b32_dpp v142, v143 row_ror:8 row_mask:0xf bank_mask:0xf
	v_mov_b32_e32 v143, 0
	v_cndmask_b32_e32 v145, v135, v137, vcc
	v_lshl_add_u64 v[136:137], v[186:187], 0, s[12:13]
	v_mov_b32_dpp v143, v134 row_ror:8 row_mask:0xf bank_mask:0xf
	v_pk_add_f32 v[134:135], v[144:145], v[142:143]
	v_pk_add_f32 v[134:135], v[188:189], v[134:135]
	global_store_dwordx2 v[136:137], v[134:135], off
	s_mov_b32 s12, s14
	s_cbranch_scc1 .LBB0_1587
	s_waitcnt vmcnt(0)
